# P1 rows interleaved across waves (stride 512 rows within a batch) so that concurrent waves cover consecutive 4 KiB rows: HBM channel spreading
# speedup vs baseline: 1.0018x; 1.0010x over previous
; __device__ __forceinline__ void p1_rows(const Args& A, int lane, int wave) {
;     ...
;     const int gw = blockIdx.x * 8 + wave, NGW = gridDim.x * 8;
;     bf16_t* HB = (bf16_t*)(ws + WS_HB);
;     f32x4 nx[4];
;     if (gw < M) {
; #pragma unroll
;         for (int j = 0; j < 4; ++j) nx[j] = ((const f32x4*)(A.x + (size_t)gw * DM) + lane)[64 * j]; }
;     for (int m = gw; m < M; m += NGW) {
;         const int b = m >> 13;
;         f32x4 v[4]; float s = 0.f;
; #pragma unroll
;         for (int j = 0; j < 4; ++j) v[j] = nx[j];
;         if (m + NGW < M) {
; #pragma unroll
;             for (int j = 0; j < 4; ++j) nx[j] = ((const f32x4*)(A.x + (size_t)(m + NGW) * DM) + lane)[64 * j]; }
; #pragma unroll
;         for (int j = 0; j < 4; ++j) s += (v[j][0] * v[j][0] + v[j][1] * v[j][1]) + (v[j][2] * v[j][2] + v[j][3] * v[j][3]);
;         const float rstd = 1.0f / sqrtf(wave_sum(s) * (1.0f / DM) + RMS_EPS);
.LBB0_137:
	s_cmp_lt_i32 s48, 2
	s_cselect_b64 s[2:3], -1, 0
	s_and_b64 s[2:3], s[2:3], s[0:1]
	s_andn2_b64 vcc, exec, s[2:3]
	s_cbranch_vccnz .LBB0_148
	v_readlane_b32 s0, v254, 1
	v_readlane_b32 s1, v254, 2
	s_load_dwordx2 s[4:5], s[0:1], 0x98
	s_lshl_b32 s0, s87, 3
	v_readlane_b32 s1, v254, 7
	s_add_i32 s6, s1, s0
	s_lshl_b32 s8, s33, 3
	s_cmpk_gt_i32 s6, 0x7fff
	v_lshlrev_b32_e32 v34, 3, v220
	s_cbranch_scc1 .LBB0_143
	v_readlane_b32 s10, v254, 1
	v_readlane_b32 s11, v254, 2
	s_nop 0
	s_load_dwordx2 s[0:1], s[10:11], 0x0
	s_load_dwordx2 s[12:13], s[10:11], 0x20
	v_lshlrev_b32_e32 v200, 4, v220
	v_xor_b32_e32 v201, 16, v220
	v_xor_b32_e32 v202, 32, v220
	v_lshlrev_b32_e32 v201, 2, v201
	v_lshlrev_b32_e32 v202, 2, v202
	v_mov_b32_e32 v203, 0x260
	v_mov_b32_e32 v204, 0x358637bd
	s_mov_b32 s20, 0xf800000
	s_waitcnt lgkmcnt(0)
	s_lshr_b32 s7, s6, 9
	s_lshl_b32 s7, s7, 13
	s_and_b32 s21, s6, 0x1ff
	s_add_u32 s21, s7, s21
	s_lshl_b32 s7, s21, 12
	s_add_u32 s14, s0, s7
	s_addc_u32 s15, s1, 0
	s_lshl_b32 s7, s21, 11
	s_add_u32 s16, s4, 0x4000000
	s_addc_u32 s17, s5, 0
	s_add_u32 s16, s16, s7
	s_addc_u32 s17, s17, 0
	s_lshr_b32 s7, s6, 9
	s_mul_i32 s7, s7, 0x9000
	s_add_u32 s18, s4, s7
	s_addc_u32 s19, s5, 0
	s_add_u32 s22, s18, 0x1000
	s_addc_u32 s23, s19, 0
	global_load_dwordx4 v[64:67], v200, s[12:13]
	global_load_dwordx4 v[68:71], v200, s[12:13] offset:1024
	global_load_dwordx4 v[72:75], v200, s[12:13] offset:2048
	global_load_dwordx4 v[76:79], v200, s[12:13] offset:3072
	global_load_dwordx4 v[80:83], v200, s[22:23]
	global_load_dwordx4 v[84:87], v200, s[22:23] offset:1024
	global_load_dwordx4 v[88:91], v200, s[22:23] offset:2048
	global_load_dwordx4 v[92:95], v200, s[22:23] offset:3072
	global_load_dwordx4 v[96:99], v200, s[18:19]
	global_load_dwordx4 v[100:103], v200, s[18:19] offset:1024
	global_load_dwordx4 v[104:107], v200, s[18:19] offset:2048
	global_load_dwordx4 v[108:111], v200, s[18:19] offset:3072
	global_load_dwordx4 v[112:115], v200, s[14:15]
	global_load_dwordx4 v[116:119], v200, s[14:15] offset:1024
	global_load_dwordx4 v[120:123], v200, s[14:15] offset:2048
	global_load_dwordx4 v[124:127], v200, s[14:15] offset:3072
	s_add_u32 s14, s14, 0x200000
	s_addc_u32 s15, s15, 0
	global_load_dwordx4 v[128:131], v200, s[14:15]
	global_load_dwordx4 v[132:135], v200, s[14:15] offset:1024
	global_load_dwordx4 v[136:139], v200, s[14:15] offset:2048
	global_load_dwordx4 v[140:143], v200, s[14:15] offset:3072
	s_add_u32 s14, s14, 0x200000
	s_addc_u32 s15, s15, 0
	global_load_dwordx4 v[144:147], v200, s[14:15]
	global_load_dwordx4 v[148:151], v200, s[14:15] offset:1024
	global_load_dwordx4 v[152:155], v200, s[14:15] offset:2048
	global_load_dwordx4 v[156:159], v200, s[14:15] offset:3072
	s_add_u32 s14, s14, 0x200000
	s_addc_u32 s15, s15, 0
	global_load_dwordx4 v[160:163], v200, s[14:15]
	global_load_dwordx4 v[164:167], v200, s[14:15] offset:1024
	global_load_dwordx4 v[168:171], v200, s[14:15] offset:2048
	global_load_dwordx4 v[172:175], v200, s[14:15] offset:3072
	s_add_u32 s14, s14, 0x200000
	s_addc_u32 s15, s15, 0
	s_waitcnt vmcnt(12)
	v_pk_add_f32 v[80:81], v[80:81], 1.0 op_sel_hi:[1,0]
	v_pk_add_f32 v[82:83], v[82:83], 1.0 op_sel_hi:[1,0]
	v_pk_add_f32 v[84:85], v[84:85], 1.0 op_sel_hi:[1,0]
	v_pk_add_f32 v[86:87], v[86:87], 1.0 op_sel_hi:[1,0]
	v_pk_add_f32 v[88:89], v[88:89], 1.0 op_sel_hi:[1,0]
	v_pk_add_f32 v[90:91], v[90:91], 1.0 op_sel_hi:[1,0]
	v_pk_add_f32 v[92:93], v[92:93], 1.0 op_sel_hi:[1,0]
	v_pk_add_f32 v[94:95], v[94:95], 1.0 op_sel_hi:[1,0]
	v_mul_f32_e32 v177, v112, v112
	v_mul_f32_e32 v178, v114, v114
	v_fmac_f32_e32 v177, v113, v113
	v_fmac_f32_e32 v178, v115, v115
	v_add_f32_e32 v176, v177, v178
	v_mul_f32_e32 v177, v116, v116
	v_mul_f32_e32 v178, v118, v118
	v_fmac_f32_e32 v177, v117, v117
	v_fmac_f32_e32 v178, v119, v119
	v_add_f32_e32 v177, v177, v178
	v_add_f32_e32 v176, v176, v177
	v_mul_f32_e32 v177, v120, v120
	v_mul_f32_e32 v178, v122, v122
	v_fmac_f32_e32 v177, v121, v121
	v_fmac_f32_e32 v178, v123, v123
	v_add_f32_e32 v177, v177, v178
	v_add_f32_e32 v176, v176, v177
	v_mul_f32_e32 v177, v124, v124
	v_mul_f32_e32 v178, v126, v126
	v_fmac_f32_e32 v177, v125, v125
	v_fmac_f32_e32 v178, v127, v127
	v_add_f32_e32 v177, v177, v178
	v_add_f32_e32 v176, v176, v177
	s_nop 1
	v_add_f32_dpp v176, v176, v176 quad_perm:[1,0,3,2] row_mask:0xf bank_mask:0xf
	s_nop 1
	v_add_f32_dpp v176, v176, v176 quad_perm:[2,3,0,1] row_mask:0xf bank_mask:0xf
	s_nop 1
	v_add_f32_dpp v176, v176, v176 row_half_mirror row_mask:0xf bank_mask:0xf
	s_nop 1
	v_add_f32_dpp v176, v176, v176 row_mirror row_mask:0xf bank_mask:0xf
	ds_bpermute_b32 v177, v201, v176
	s_waitcnt lgkmcnt(0)
	v_add_f32_e32 v176, v176, v177
	ds_bpermute_b32 v177, v202, v176
	s_waitcnt lgkmcnt(0)
; __device__ __forceinline__ unsigned cvt_pk_bf16(float lo, float hi) { unsigned r; asm volatile("v_cvt_pk_bf16_f32 %0, %1, %2" : "=v"(r) : "v"(lo), "v"(hi)); return r; }
; __device__ __forceinline__ void p1_rows(const Args& A, int lane, int wave) {
;     ...
;         if (m + NGW < M) {
; #pragma unroll
;             for (int j = 0; j < 4; ++j) nx[j] = ((const f32x4*)(A.x + (size_t)(m + NGW) * DM) + lane)[64 * j]; }
; #pragma unroll
;         for (int j = 0; j < 4; ++j) s += (v[j][0] * v[j][0] + v[j][1] * v[j][1]) + (v[j][2] * v[j][2] + v[j][3] * v[j][3]);
;         const float rstd = 1.0f / sqrtf(wave_sum(s) * (1.0f / DM) + RMS_EPS);
;         u32x2* o8 = (u32x2*)(HB + (size_t)m * DM) + lane;
; #pragma unroll
;         for (int j = 0; j < 4; ++j) { const int c = 4 * lane + 256 * j;
;             const f32x4 g = *(const f32x4*)(A.g_ffn1 + c), sc = *(const f32x4*)(mods + (size_t)b * NMODC + MOD_SC1 * DM + c), sh = *(const f32x4*)(mods + (size_t)b * NMODC + MOD_SH1 * DM + c);
;             const f32x4 h = (v[j] * rstd) * g * (sc + 1.0f) + sh;
;             u32x2 w; w.x = pg8::cvt_pk_bf16(h[0], h[1]); w.y = pg8::cvt_pk_bf16(h[2], h[3]); o8[64 * j] = w; }
	v_add_f32_e32 v176, v176, v177
	v_fmamk_f32 v176, v176, 0x3a800000, v204
	v_mul_f32_e32 v179, 0x4f800000, v176
	v_cmp_gt_f32_e32 vcc, s20, v176
	s_nop 1
	v_cndmask_b32_e32 v176, v176, v179, vcc
	v_sqrt_f32_e32 v179, v176
	s_nop 0
	v_add_u32_e32 v180, -1, v179
	v_add_u32_e32 v181, 1, v179
	v_fma_f32 v182, -v180, v179, v176
	v_fma_f32 v183, -v181, v179, v176
	v_cmp_ge_f32_e64 s[0:1], 0, v182
	s_nop 1
	v_cndmask_b32_e64 v179, v179, v180, s[0:1]
	v_cmp_lt_f32_e64 s[0:1], 0, v183
	s_nop 1
	v_cndmask_b32_e64 v179, v179, v181, s[0:1]
	v_mul_f32_e32 v180, 0x37800000, v179
	v_cndmask_b32_e32 v179, v179, v180, vcc
	v_cmp_class_f32_e32 vcc, v176, v203
	s_nop 1
	v_cndmask_b32_e32 v176, v179, v176, vcc
	v_div_scale_f32 v179, s[0:1], v176, v176, 1.0
	v_rcp_f32_e32 v180, v179
	v_div_scale_f32 v181, vcc, 1.0, v176, 1.0
	v_fma_f32 v182, -v179, v180, 1.0
	v_fmac_f32_e32 v180, v182, v180
	v_mul_f32_e32 v182, v181, v180
	v_fma_f32 v183, -v179, v182, v181
	v_fmac_f32_e32 v182, v183, v180
	v_fma_f32 v179, -v179, v182, v181
	v_div_fmas_f32 v179, v179, v180, v182
	v_div_fixup_f32 v206, v179, v176, 1.0
	v_pk_mul_f32 v[112:113], v[112:113], v[206:207] op_sel_hi:[1,0]
	v_pk_mul_f32 v[114:115], v[114:115], v[206:207] op_sel_hi:[1,0]
	v_pk_mul_f32 v[112:113], v[64:65], v[112:113]
	v_pk_mul_f32 v[114:115], v[66:67], v[114:115]
	v_pk_fma_f32 v[112:113], v[80:81], v[112:113], v[96:97]
	v_pk_fma_f32 v[114:115], v[82:83], v[114:115], v[98:99]
	v_cvt_pk_bf16_f32 v184, v112, v113
	v_cvt_pk_bf16_f32 v185, v114, v115
	global_store_dwordx2 v34, v[184:185], s[16:17]
	v_pk_mul_f32 v[116:117], v[116:117], v[206:207] op_sel_hi:[1,0]
	v_pk_mul_f32 v[118:119], v[118:119], v[206:207] op_sel_hi:[1,0]
	v_pk_mul_f32 v[116:117], v[68:69], v[116:117]
	v_pk_mul_f32 v[118:119], v[70:71], v[118:119]
	v_pk_fma_f32 v[116:117], v[84:85], v[116:117], v[100:101]
	v_pk_fma_f32 v[118:119], v[86:87], v[118:119], v[102:103]
	v_cvt_pk_bf16_f32 v186, v116, v117
	v_cvt_pk_bf16_f32 v187, v118, v119
	global_store_dwordx2 v34, v[186:187], s[16:17] offset:512
	v_pk_mul_f32 v[120:121], v[120:121], v[206:207] op_sel_hi:[1,0]
	v_pk_mul_f32 v[122:123], v[122:123], v[206:207] op_sel_hi:[1,0]
	v_pk_mul_f32 v[120:121], v[72:73], v[120:121]
	v_pk_mul_f32 v[122:123], v[74:75], v[122:123]
	v_pk_fma_f32 v[120:121], v[88:89], v[120:121], v[104:105]
	v_pk_fma_f32 v[122:123], v[90:91], v[122:123], v[106:107]
	v_cvt_pk_bf16_f32 v188, v120, v121
	v_cvt_pk_bf16_f32 v189, v122, v123
	global_store_dwordx2 v34, v[188:189], s[16:17] offset:1024
	v_pk_mul_f32 v[124:125], v[124:125], v[206:207] op_sel_hi:[1,0]
	v_pk_mul_f32 v[126:127], v[126:127], v[206:207] op_sel_hi:[1,0]
	v_pk_mul_f32 v[124:125], v[76:77], v[124:125]
	v_pk_mul_f32 v[126:127], v[78:79], v[126:127]
	v_pk_fma_f32 v[124:125], v[92:93], v[124:125], v[108:109]
	v_pk_fma_f32 v[126:127], v[94:95], v[126:127], v[110:111]
	v_cvt_pk_bf16_f32 v190, v124, v125
	v_cvt_pk_bf16_f32 v191, v126, v127
	global_store_dwordx2 v34, v[190:191], s[16:17] offset:1536
	s_add_u32 s16, s16, 0x100000
	s_addc_u32 s17, s17, 0
	global_load_dwordx4 v[112:115], v200, s[14:15]
	global_load_dwordx4 v[116:119], v200, s[14:15] offset:1024
	global_load_dwordx4 v[120:123], v200, s[14:15] offset:2048
	global_load_dwordx4 v[124:127], v200, s[14:15] offset:3072
	s_add_u32 s14, s14, 0x200000
	s_addc_u32 s15, s15, 0
	s_waitcnt vmcnt(16)
	v_mul_f32_e32 v177, v128, v128
	v_mul_f32_e32 v178, v130, v130
	v_fmac_f32_e32 v177, v129, v129
	v_fmac_f32_e32 v178, v131, v131
	v_add_f32_e32 v176, v177, v178
	v_mul_f32_e32 v177, v132, v132
	v_mul_f32_e32 v178, v134, v134
	v_fmac_f32_e32 v177, v133, v133
	v_fmac_f32_e32 v178, v135, v135
	v_add_f32_e32 v177, v177, v178
	v_add_f32_e32 v176, v176, v177
	v_mul_f32_e32 v177, v136, v136
	v_mul_f32_e32 v178, v138, v138
	v_fmac_f32_e32 v177, v137, v137
	v_fmac_f32_e32 v178, v139, v139
	v_add_f32_e32 v177, v177, v178
	v_add_f32_e32 v176, v176, v177
	v_mul_f32_e32 v177, v140, v140
	v_mul_f32_e32 v178, v142, v142
	v_fmac_f32_e32 v177, v141, v141
	v_fmac_f32_e32 v178, v143, v143
	v_add_f32_e32 v177, v177, v178
	v_add_f32_e32 v176, v176, v177
	s_nop 1
	v_add_f32_dpp v176, v176, v176 quad_perm:[1,0,3,2] row_mask:0xf bank_mask:0xf
	s_nop 1
	v_add_f32_dpp v176, v176, v176 quad_perm:[2,3,0,1] row_mask:0xf bank_mask:0xf
	s_nop 1
	v_add_f32_dpp v176, v176, v176 row_half_mirror row_mask:0xf bank_mask:0xf
	s_nop 1
	v_add_f32_dpp v176, v176, v176 row_mirror row_mask:0xf bank_mask:0xf
	ds_bpermute_b32 v177, v201, v176
	s_waitcnt lgkmcnt(0)
	v_add_f32_e32 v176, v176, v177
	ds_bpermute_b32 v177, v202, v176
	s_waitcnt lgkmcnt(0)
; __device__ __forceinline__ unsigned cvt_pk_bf16(float lo, float hi) { unsigned r; asm volatile("v_cvt_pk_bf16_f32 %0, %1, %2" : "=v"(r) : "v"(lo), "v"(hi)); return r; }
; __device__ __forceinline__ void p1_rows(const Args& A, int lane, int wave) {
;     ...
;         if (m + NGW < M) {
; #pragma unroll
;             for (int j = 0; j < 4; ++j) nx[j] = ((const f32x4*)(A.x + (size_t)(m + NGW) * DM) + lane)[64 * j]; }
; #pragma unroll
;         for (int j = 0; j < 4; ++j) s += (v[j][0] * v[j][0] + v[j][1] * v[j][1]) + (v[j][2] * v[j][2] + v[j][3] * v[j][3]);
;         const float rstd = 1.0f / sqrtf(wave_sum(s) * (1.0f / DM) + RMS_EPS);
;         u32x2* o8 = (u32x2*)(HB + (size_t)m * DM) + lane;
; #pragma unroll
;         for (int j = 0; j < 4; ++j) { const int c = 4 * lane + 256 * j;
;             const f32x4 g = *(const f32x4*)(A.g_ffn1 + c), sc = *(const f32x4*)(mods + (size_t)b * NMODC + MOD_SC1 * DM + c), sh = *(const f32x4*)(mods + (size_t)b * NMODC + MOD_SH1 * DM + c);
;             const f32x4 h = (v[j] * rstd) * g * (sc + 1.0f) + sh;
;             u32x2 w; w.x = pg8::cvt_pk_bf16(h[0], h[1]); w.y = pg8::cvt_pk_bf16(h[2], h[3]); o8[64 * j] = w; }
	v_add_f32_e32 v176, v176, v177
	v_fmamk_f32 v176, v176, 0x3a800000, v204
	v_mul_f32_e32 v179, 0x4f800000, v176
	v_cmp_gt_f32_e32 vcc, s20, v176
	s_nop 1
	v_cndmask_b32_e32 v176, v176, v179, vcc
	v_sqrt_f32_e32 v179, v176
	s_nop 0
	v_add_u32_e32 v180, -1, v179
	v_add_u32_e32 v181, 1, v179
	v_fma_f32 v182, -v180, v179, v176
	v_fma_f32 v183, -v181, v179, v176
	v_cmp_ge_f32_e64 s[0:1], 0, v182
	s_nop 1
	v_cndmask_b32_e64 v179, v179, v180, s[0:1]
	v_cmp_lt_f32_e64 s[0:1], 0, v183
	s_nop 1
	v_cndmask_b32_e64 v179, v179, v181, s[0:1]
	v_mul_f32_e32 v180, 0x37800000, v179
	v_cndmask_b32_e32 v179, v179, v180, vcc
	v_cmp_class_f32_e32 vcc, v176, v203
	s_nop 1
	v_cndmask_b32_e32 v176, v179, v176, vcc
	v_div_scale_f32 v179, s[0:1], v176, v176, 1.0
	v_rcp_f32_e32 v180, v179
	v_div_scale_f32 v181, vcc, 1.0, v176, 1.0
	v_fma_f32 v182, -v179, v180, 1.0
	v_fmac_f32_e32 v180, v182, v180
	v_mul_f32_e32 v182, v181, v180
	v_fma_f32 v183, -v179, v182, v181
	v_fmac_f32_e32 v182, v183, v180
	v_fma_f32 v179, -v179, v182, v181
	v_div_fmas_f32 v179, v179, v180, v182
	v_div_fixup_f32 v206, v179, v176, 1.0
	v_pk_mul_f32 v[128:129], v[128:129], v[206:207] op_sel_hi:[1,0]
	v_pk_mul_f32 v[130:131], v[130:131], v[206:207] op_sel_hi:[1,0]
	v_pk_mul_f32 v[128:129], v[64:65], v[128:129]
	v_pk_mul_f32 v[130:131], v[66:67], v[130:131]
	v_pk_fma_f32 v[128:129], v[80:81], v[128:129], v[96:97]
	v_pk_fma_f32 v[130:131], v[82:83], v[130:131], v[98:99]
	v_cvt_pk_bf16_f32 v192, v128, v129
	v_cvt_pk_bf16_f32 v193, v130, v131
	global_store_dwordx2 v34, v[192:193], s[16:17]
	v_pk_mul_f32 v[132:133], v[132:133], v[206:207] op_sel_hi:[1,0]
	v_pk_mul_f32 v[134:135], v[134:135], v[206:207] op_sel_hi:[1,0]
	v_pk_mul_f32 v[132:133], v[68:69], v[132:133]
	v_pk_mul_f32 v[134:135], v[70:71], v[134:135]
	v_pk_fma_f32 v[132:133], v[84:85], v[132:133], v[100:101]
	v_pk_fma_f32 v[134:135], v[86:87], v[134:135], v[102:103]
	v_cvt_pk_bf16_f32 v194, v132, v133
	v_cvt_pk_bf16_f32 v195, v134, v135
	global_store_dwordx2 v34, v[194:195], s[16:17] offset:512
	v_pk_mul_f32 v[136:137], v[136:137], v[206:207] op_sel_hi:[1,0]
	v_pk_mul_f32 v[138:139], v[138:139], v[206:207] op_sel_hi:[1,0]
	v_pk_mul_f32 v[136:137], v[72:73], v[136:137]
	v_pk_mul_f32 v[138:139], v[74:75], v[138:139]
	v_pk_fma_f32 v[136:137], v[88:89], v[136:137], v[104:105]
	v_pk_fma_f32 v[138:139], v[90:91], v[138:139], v[106:107]
	v_cvt_pk_bf16_f32 v196, v136, v137
	v_cvt_pk_bf16_f32 v197, v138, v139
	global_store_dwordx2 v34, v[196:197], s[16:17] offset:1024
	v_pk_mul_f32 v[140:141], v[140:141], v[206:207] op_sel_hi:[1,0]
	v_pk_mul_f32 v[142:143], v[142:143], v[206:207] op_sel_hi:[1,0]
	v_pk_mul_f32 v[140:141], v[76:77], v[140:141]
	v_pk_mul_f32 v[142:143], v[78:79], v[142:143]
	v_pk_fma_f32 v[140:141], v[92:93], v[140:141], v[108:109]
	v_pk_fma_f32 v[142:143], v[94:95], v[142:143], v[110:111]
	v_cvt_pk_bf16_f32 v198, v140, v141
	v_cvt_pk_bf16_f32 v199, v142, v143
	global_store_dwordx2 v34, v[198:199], s[16:17] offset:1536
	s_add_u32 s16, s16, 0x100000
	s_addc_u32 s17, s17, 0
	global_load_dwordx4 v[128:131], v200, s[14:15]
	global_load_dwordx4 v[132:135], v200, s[14:15] offset:1024
	global_load_dwordx4 v[136:139], v200, s[14:15] offset:2048
	global_load_dwordx4 v[140:143], v200, s[14:15] offset:3072
	s_add_u32 s14, s14, 0x200000
	s_addc_u32 s15, s15, 0
	s_waitcnt vmcnt(20)
	v_mul_f32_e32 v177, v144, v144
	v_mul_f32_e32 v178, v146, v146
	v_fmac_f32_e32 v177, v145, v145
	v_fmac_f32_e32 v178, v147, v147
	v_add_f32_e32 v176, v177, v178
	v_mul_f32_e32 v177, v148, v148
	v_mul_f32_e32 v178, v150, v150
	v_fmac_f32_e32 v177, v149, v149
	v_fmac_f32_e32 v178, v151, v151
	v_add_f32_e32 v177, v177, v178
	v_add_f32_e32 v176, v176, v177
	v_mul_f32_e32 v177, v152, v152
	v_mul_f32_e32 v178, v154, v154
	v_fmac_f32_e32 v177, v153, v153
	v_fmac_f32_e32 v178, v155, v155
	v_add_f32_e32 v177, v177, v178
	v_add_f32_e32 v176, v176, v177
	v_mul_f32_e32 v177, v156, v156
	v_mul_f32_e32 v178, v158, v158
	v_fmac_f32_e32 v177, v157, v157
	v_fmac_f32_e32 v178, v159, v159
	v_add_f32_e32 v177, v177, v178
	v_add_f32_e32 v176, v176, v177
	s_nop 1
	v_add_f32_dpp v176, v176, v176 quad_perm:[1,0,3,2] row_mask:0xf bank_mask:0xf
	s_nop 1
	v_add_f32_dpp v176, v176, v176 quad_perm:[2,3,0,1] row_mask:0xf bank_mask:0xf
	s_nop 1
	v_add_f32_dpp v176, v176, v176 row_half_mirror row_mask:0xf bank_mask:0xf
	s_nop 1
	v_add_f32_dpp v176, v176, v176 row_mirror row_mask:0xf bank_mask:0xf
	ds_bpermute_b32 v177, v201, v176
	s_waitcnt lgkmcnt(0)
	v_add_f32_e32 v176, v176, v177
	ds_bpermute_b32 v177, v202, v176
	s_waitcnt lgkmcnt(0)
; __device__ __forceinline__ unsigned cvt_pk_bf16(float lo, float hi) { unsigned r; asm volatile("v_cvt_pk_bf16_f32 %0, %1, %2" : "=v"(r) : "v"(lo), "v"(hi)); return r; }
; __device__ __forceinline__ void p1_rows(const Args& A, int lane, int wave) {
;     ...
;         if (m + NGW < M) {
; #pragma unroll
;             for (int j = 0; j < 4; ++j) nx[j] = ((const f32x4*)(A.x + (size_t)(m + NGW) * DM) + lane)[64 * j]; }
; #pragma unroll
;         for (int j = 0; j < 4; ++j) s += (v[j][0] * v[j][0] + v[j][1] * v[j][1]) + (v[j][2] * v[j][2] + v[j][3] * v[j][3]);
;         const float rstd = 1.0f / sqrtf(wave_sum(s) * (1.0f / DM) + RMS_EPS);
;         u32x2* o8 = (u32x2*)(HB + (size_t)m * DM) + lane;
; #pragma unroll
;         for (int j = 0; j < 4; ++j) { const int c = 4 * lane + 256 * j;
;             const f32x4 g = *(const f32x4*)(A.g_ffn1 + c), sc = *(const f32x4*)(mods + (size_t)b * NMODC + MOD_SC1 * DM + c), sh = *(const f32x4*)(mods + (size_t)b * NMODC + MOD_SH1 * DM + c);
;             const f32x4 h = (v[j] * rstd) * g * (sc + 1.0f) + sh;
;             u32x2 w; w.x = pg8::cvt_pk_bf16(h[0], h[1]); w.y = pg8::cvt_pk_bf16(h[2], h[3]); o8[64 * j] = w; }
	v_add_f32_e32 v176, v176, v177
	v_fmamk_f32 v176, v176, 0x3a800000, v204
	v_mul_f32_e32 v179, 0x4f800000, v176
	v_cmp_gt_f32_e32 vcc, s20, v176
	s_nop 1
	v_cndmask_b32_e32 v176, v176, v179, vcc
	v_sqrt_f32_e32 v179, v176
	s_nop 0
	v_add_u32_e32 v180, -1, v179
	v_add_u32_e32 v181, 1, v179
	v_fma_f32 v182, -v180, v179, v176
	v_fma_f32 v183, -v181, v179, v176
	v_cmp_ge_f32_e64 s[0:1], 0, v182
	s_nop 1
	v_cndmask_b32_e64 v179, v179, v180, s[0:1]
	v_cmp_lt_f32_e64 s[0:1], 0, v183
	s_nop 1
	v_cndmask_b32_e64 v179, v179, v181, s[0:1]
	v_mul_f32_e32 v180, 0x37800000, v179
	v_cndmask_b32_e32 v179, v179, v180, vcc
	v_cmp_class_f32_e32 vcc, v176, v203
	s_nop 1
	v_cndmask_b32_e32 v176, v179, v176, vcc
	v_div_scale_f32 v179, s[0:1], v176, v176, 1.0
	v_rcp_f32_e32 v180, v179
	v_div_scale_f32 v181, vcc, 1.0, v176, 1.0
	v_fma_f32 v182, -v179, v180, 1.0
	v_fmac_f32_e32 v180, v182, v180
	v_mul_f32_e32 v182, v181, v180
	v_fma_f32 v183, -v179, v182, v181
	v_fmac_f32_e32 v182, v183, v180
	v_fma_f32 v179, -v179, v182, v181
	v_div_fmas_f32 v179, v179, v180, v182
	v_div_fixup_f32 v206, v179, v176, 1.0
	v_pk_mul_f32 v[144:145], v[144:145], v[206:207] op_sel_hi:[1,0]
	v_pk_mul_f32 v[146:147], v[146:147], v[206:207] op_sel_hi:[1,0]
	v_pk_mul_f32 v[144:145], v[64:65], v[144:145]
	v_pk_mul_f32 v[146:147], v[66:67], v[146:147]
	v_pk_fma_f32 v[144:145], v[80:81], v[144:145], v[96:97]
	v_pk_fma_f32 v[146:147], v[82:83], v[146:147], v[98:99]
	v_cvt_pk_bf16_f32 v184, v144, v145
	v_cvt_pk_bf16_f32 v185, v146, v147
	global_store_dwordx2 v34, v[184:185], s[16:17]
	v_pk_mul_f32 v[148:149], v[148:149], v[206:207] op_sel_hi:[1,0]
	v_pk_mul_f32 v[150:151], v[150:151], v[206:207] op_sel_hi:[1,0]
	v_pk_mul_f32 v[148:149], v[68:69], v[148:149]
	v_pk_mul_f32 v[150:151], v[70:71], v[150:151]
	v_pk_fma_f32 v[148:149], v[84:85], v[148:149], v[100:101]
	v_pk_fma_f32 v[150:151], v[86:87], v[150:151], v[102:103]
	v_cvt_pk_bf16_f32 v186, v148, v149
	v_cvt_pk_bf16_f32 v187, v150, v151
	global_store_dwordx2 v34, v[186:187], s[16:17] offset:512
	v_pk_mul_f32 v[152:153], v[152:153], v[206:207] op_sel_hi:[1,0]
	v_pk_mul_f32 v[154:155], v[154:155], v[206:207] op_sel_hi:[1,0]
	v_pk_mul_f32 v[152:153], v[72:73], v[152:153]
	v_pk_mul_f32 v[154:155], v[74:75], v[154:155]
	v_pk_fma_f32 v[152:153], v[88:89], v[152:153], v[104:105]
	v_pk_fma_f32 v[154:155], v[90:91], v[154:155], v[106:107]
	v_cvt_pk_bf16_f32 v188, v152, v153
	v_cvt_pk_bf16_f32 v189, v154, v155
	global_store_dwordx2 v34, v[188:189], s[16:17] offset:1024
	v_pk_mul_f32 v[156:157], v[156:157], v[206:207] op_sel_hi:[1,0]
	v_pk_mul_f32 v[158:159], v[158:159], v[206:207] op_sel_hi:[1,0]
	v_pk_mul_f32 v[156:157], v[76:77], v[156:157]
	v_pk_mul_f32 v[158:159], v[78:79], v[158:159]
	v_pk_fma_f32 v[156:157], v[92:93], v[156:157], v[108:109]
	v_pk_fma_f32 v[158:159], v[94:95], v[158:159], v[110:111]
	v_cvt_pk_bf16_f32 v190, v156, v157
	v_cvt_pk_bf16_f32 v191, v158, v159
	global_store_dwordx2 v34, v[190:191], s[16:17] offset:1536
	s_add_u32 s16, s16, 0x100000
	s_addc_u32 s17, s17, 0
	global_load_dwordx4 v[144:147], v200, s[14:15]
	global_load_dwordx4 v[148:151], v200, s[14:15] offset:1024
	global_load_dwordx4 v[152:155], v200, s[14:15] offset:2048
	global_load_dwordx4 v[156:159], v200, s[14:15] offset:3072
	s_add_u32 s14, s14, 0x200000
	s_addc_u32 s15, s15, 0
	s_waitcnt vmcnt(24)
	v_mul_f32_e32 v177, v160, v160
	v_mul_f32_e32 v178, v162, v162
	v_fmac_f32_e32 v177, v161, v161
	v_fmac_f32_e32 v178, v163, v163
	v_add_f32_e32 v176, v177, v178
	v_mul_f32_e32 v177, v164, v164
	v_mul_f32_e32 v178, v166, v166
	v_fmac_f32_e32 v177, v165, v165
	v_fmac_f32_e32 v178, v167, v167
	v_add_f32_e32 v177, v177, v178
	v_add_f32_e32 v176, v176, v177
	v_mul_f32_e32 v177, v168, v168
	v_mul_f32_e32 v178, v170, v170
	v_fmac_f32_e32 v177, v169, v169
	v_fmac_f32_e32 v178, v171, v171
	v_add_f32_e32 v177, v177, v178
	v_add_f32_e32 v176, v176, v177
	v_mul_f32_e32 v177, v172, v172
	v_mul_f32_e32 v178, v174, v174
	v_fmac_f32_e32 v177, v173, v173
	v_fmac_f32_e32 v178, v175, v175
	v_add_f32_e32 v177, v177, v178
	v_add_f32_e32 v176, v176, v177
	s_nop 1
	v_add_f32_dpp v176, v176, v176 quad_perm:[1,0,3,2] row_mask:0xf bank_mask:0xf
	s_nop 1
	v_add_f32_dpp v176, v176, v176 quad_perm:[2,3,0,1] row_mask:0xf bank_mask:0xf
	s_nop 1
	v_add_f32_dpp v176, v176, v176 row_half_mirror row_mask:0xf bank_mask:0xf
	s_nop 1
	v_add_f32_dpp v176, v176, v176 row_mirror row_mask:0xf bank_mask:0xf
	ds_bpermute_b32 v177, v201, v176
	s_waitcnt lgkmcnt(0)
	v_add_f32_e32 v176, v176, v177
	ds_bpermute_b32 v177, v202, v176
	s_waitcnt lgkmcnt(0)
; __device__ __forceinline__ unsigned cvt_pk_bf16(float lo, float hi) { unsigned r; asm volatile("v_cvt_pk_bf16_f32 %0, %1, %2" : "=v"(r) : "v"(lo), "v"(hi)); return r; }
; __device__ __forceinline__ void p1_rows(const Args& A, int lane, int wave) {
;     ...
;         if (m + NGW < M) {
; #pragma unroll
;             for (int j = 0; j < 4; ++j) nx[j] = ((const f32x4*)(A.x + (size_t)(m + NGW) * DM) + lane)[64 * j]; }
; #pragma unroll
;         for (int j = 0; j < 4; ++j) s += (v[j][0] * v[j][0] + v[j][1] * v[j][1]) + (v[j][2] * v[j][2] + v[j][3] * v[j][3]);
;         const float rstd = 1.0f / sqrtf(wave_sum(s) * (1.0f / DM) + RMS_EPS);
;         u32x2* o8 = (u32x2*)(HB + (size_t)m * DM) + lane;
; #pragma unroll
;         for (int j = 0; j < 4; ++j) { const int c = 4 * lane + 256 * j;
;             const f32x4 g = *(const f32x4*)(A.g_ffn1 + c), sc = *(const f32x4*)(mods + (size_t)b * NMODC + MOD_SC1 * DM + c), sh = *(const f32x4*)(mods + (size_t)b * NMODC + MOD_SH1 * DM + c);
;             const f32x4 h = (v[j] * rstd) * g * (sc + 1.0f) + sh;
;             u32x2 w; w.x = pg8::cvt_pk_bf16(h[0], h[1]); w.y = pg8::cvt_pk_bf16(h[2], h[3]); o8[64 * j] = w; }
	v_add_f32_e32 v176, v176, v177
	v_fmamk_f32 v176, v176, 0x3a800000, v204
	v_mul_f32_e32 v179, 0x4f800000, v176
	v_cmp_gt_f32_e32 vcc, s20, v176
	s_nop 1
	v_cndmask_b32_e32 v176, v176, v179, vcc
	v_sqrt_f32_e32 v179, v176
	s_nop 0
	v_add_u32_e32 v180, -1, v179
	v_add_u32_e32 v181, 1, v179
	v_fma_f32 v182, -v180, v179, v176
	v_fma_f32 v183, -v181, v179, v176
	v_cmp_ge_f32_e64 s[0:1], 0, v182
	s_nop 1
	v_cndmask_b32_e64 v179, v179, v180, s[0:1]
	v_cmp_lt_f32_e64 s[0:1], 0, v183
	s_nop 1
	v_cndmask_b32_e64 v179, v179, v181, s[0:1]
	v_mul_f32_e32 v180, 0x37800000, v179
	v_cndmask_b32_e32 v179, v179, v180, vcc
	v_cmp_class_f32_e32 vcc, v176, v203
	s_nop 1
	v_cndmask_b32_e32 v176, v179, v176, vcc
	v_div_scale_f32 v179, s[0:1], v176, v176, 1.0
	v_rcp_f32_e32 v180, v179
	v_div_scale_f32 v181, vcc, 1.0, v176, 1.0
	v_fma_f32 v182, -v179, v180, 1.0
	v_fmac_f32_e32 v180, v182, v180
	v_mul_f32_e32 v182, v181, v180
	v_fma_f32 v183, -v179, v182, v181
	v_fmac_f32_e32 v182, v183, v180
	v_fma_f32 v179, -v179, v182, v181
	v_div_fmas_f32 v179, v179, v180, v182
	v_div_fixup_f32 v206, v179, v176, 1.0
	v_pk_mul_f32 v[160:161], v[160:161], v[206:207] op_sel_hi:[1,0]
	v_pk_mul_f32 v[162:163], v[162:163], v[206:207] op_sel_hi:[1,0]
	v_pk_mul_f32 v[160:161], v[64:65], v[160:161]
	v_pk_mul_f32 v[162:163], v[66:67], v[162:163]
	v_pk_fma_f32 v[160:161], v[80:81], v[160:161], v[96:97]
	v_pk_fma_f32 v[162:163], v[82:83], v[162:163], v[98:99]
	v_cvt_pk_bf16_f32 v192, v160, v161
	v_cvt_pk_bf16_f32 v193, v162, v163
	global_store_dwordx2 v34, v[192:193], s[16:17]
	v_pk_mul_f32 v[164:165], v[164:165], v[206:207] op_sel_hi:[1,0]
	v_pk_mul_f32 v[166:167], v[166:167], v[206:207] op_sel_hi:[1,0]
	v_pk_mul_f32 v[164:165], v[68:69], v[164:165]
	v_pk_mul_f32 v[166:167], v[70:71], v[166:167]
	v_pk_fma_f32 v[164:165], v[84:85], v[164:165], v[100:101]
	v_pk_fma_f32 v[166:167], v[86:87], v[166:167], v[102:103]
	v_cvt_pk_bf16_f32 v194, v164, v165
	v_cvt_pk_bf16_f32 v195, v166, v167
	global_store_dwordx2 v34, v[194:195], s[16:17] offset:512
	v_pk_mul_f32 v[168:169], v[168:169], v[206:207] op_sel_hi:[1,0]
	v_pk_mul_f32 v[170:171], v[170:171], v[206:207] op_sel_hi:[1,0]
	v_pk_mul_f32 v[168:169], v[72:73], v[168:169]
	v_pk_mul_f32 v[170:171], v[74:75], v[170:171]
	v_pk_fma_f32 v[168:169], v[88:89], v[168:169], v[104:105]
	v_pk_fma_f32 v[170:171], v[90:91], v[170:171], v[106:107]
	v_cvt_pk_bf16_f32 v196, v168, v169
	v_cvt_pk_bf16_f32 v197, v170, v171
	global_store_dwordx2 v34, v[196:197], s[16:17] offset:1024
	v_pk_mul_f32 v[172:173], v[172:173], v[206:207] op_sel_hi:[1,0]
	v_pk_mul_f32 v[174:175], v[174:175], v[206:207] op_sel_hi:[1,0]
	v_pk_mul_f32 v[172:173], v[76:77], v[172:173]
	v_pk_mul_f32 v[174:175], v[78:79], v[174:175]
	v_pk_fma_f32 v[172:173], v[92:93], v[172:173], v[108:109]
	v_pk_fma_f32 v[174:175], v[94:95], v[174:175], v[110:111]
	v_cvt_pk_bf16_f32 v198, v172, v173
	v_cvt_pk_bf16_f32 v199, v174, v175
	global_store_dwordx2 v34, v[198:199], s[16:17] offset:1536
	s_add_u32 s16, s16, 0x100000
	s_addc_u32 s17, s17, 0
	global_load_dwordx4 v[160:163], v200, s[14:15]
	global_load_dwordx4 v[164:167], v200, s[14:15] offset:1024
	global_load_dwordx4 v[168:171], v200, s[14:15] offset:2048
	global_load_dwordx4 v[172:175], v200, s[14:15] offset:3072
	s_add_u32 s14, s14, 0x200000
	s_addc_u32 s15, s15, 0
	s_waitcnt vmcnt(24)
	v_mul_f32_e32 v177, v112, v112
	v_mul_f32_e32 v178, v114, v114
	v_fmac_f32_e32 v177, v113, v113
	v_fmac_f32_e32 v178, v115, v115
	v_add_f32_e32 v176, v177, v178
	v_mul_f32_e32 v177, v116, v116
	v_mul_f32_e32 v178, v118, v118
	v_fmac_f32_e32 v177, v117, v117
	v_fmac_f32_e32 v178, v119, v119
	v_add_f32_e32 v177, v177, v178
	v_add_f32_e32 v176, v176, v177
	v_mul_f32_e32 v177, v120, v120
	v_mul_f32_e32 v178, v122, v122
	v_fmac_f32_e32 v177, v121, v121
	v_fmac_f32_e32 v178, v123, v123
	v_add_f32_e32 v177, v177, v178
	v_add_f32_e32 v176, v176, v177
	v_mul_f32_e32 v177, v124, v124
	v_mul_f32_e32 v178, v126, v126
	v_fmac_f32_e32 v177, v125, v125
	v_fmac_f32_e32 v178, v127, v127
	v_add_f32_e32 v177, v177, v178
	v_add_f32_e32 v176, v176, v177
	s_nop 1
	v_add_f32_dpp v176, v176, v176 quad_perm:[1,0,3,2] row_mask:0xf bank_mask:0xf
	s_nop 1
	v_add_f32_dpp v176, v176, v176 quad_perm:[2,3,0,1] row_mask:0xf bank_mask:0xf
	s_nop 1
	v_add_f32_dpp v176, v176, v176 row_half_mirror row_mask:0xf bank_mask:0xf
	s_nop 1
	v_add_f32_dpp v176, v176, v176 row_mirror row_mask:0xf bank_mask:0xf
	ds_bpermute_b32 v177, v201, v176
	s_waitcnt lgkmcnt(0)
	v_add_f32_e32 v176, v176, v177
	ds_bpermute_b32 v177, v202, v176
	s_waitcnt lgkmcnt(0)
; __device__ __forceinline__ unsigned cvt_pk_bf16(float lo, float hi) { unsigned r; asm volatile("v_cvt_pk_bf16_f32 %0, %1, %2" : "=v"(r) : "v"(lo), "v"(hi)); return r; }
; __device__ __forceinline__ void p1_rows(const Args& A, int lane, int wave) {
;     ...
;         if (m + NGW < M) {
; #pragma unroll
;             for (int j = 0; j < 4; ++j) nx[j] = ((const f32x4*)(A.x + (size_t)(m + NGW) * DM) + lane)[64 * j]; }
; #pragma unroll
;         for (int j = 0; j < 4; ++j) s += (v[j][0] * v[j][0] + v[j][1] * v[j][1]) + (v[j][2] * v[j][2] + v[j][3] * v[j][3]);
;         const float rstd = 1.0f / sqrtf(wave_sum(s) * (1.0f / DM) + RMS_EPS);
;         u32x2* o8 = (u32x2*)(HB + (size_t)m * DM) + lane;
; #pragma unroll
;         for (int j = 0; j < 4; ++j) { const int c = 4 * lane + 256 * j;
;             const f32x4 g = *(const f32x4*)(A.g_ffn1 + c), sc = *(const f32x4*)(mods + (size_t)b * NMODC + MOD_SC1 * DM + c), sh = *(const f32x4*)(mods + (size_t)b * NMODC + MOD_SH1 * DM + c);
;             const f32x4 h = (v[j] * rstd) * g * (sc + 1.0f) + sh;
;             u32x2 w; w.x = pg8::cvt_pk_bf16(h[0], h[1]); w.y = pg8::cvt_pk_bf16(h[2], h[3]); o8[64 * j] = w; }
	v_add_f32_e32 v176, v176, v177
	v_fmamk_f32 v176, v176, 0x3a800000, v204
	v_mul_f32_e32 v179, 0x4f800000, v176
	v_cmp_gt_f32_e32 vcc, s20, v176
	s_nop 1
	v_cndmask_b32_e32 v176, v176, v179, vcc
	v_sqrt_f32_e32 v179, v176
	s_nop 0
	v_add_u32_e32 v180, -1, v179
	v_add_u32_e32 v181, 1, v179
	v_fma_f32 v182, -v180, v179, v176
	v_fma_f32 v183, -v181, v179, v176
	v_cmp_ge_f32_e64 s[0:1], 0, v182
	s_nop 1
	v_cndmask_b32_e64 v179, v179, v180, s[0:1]
	v_cmp_lt_f32_e64 s[0:1], 0, v183
	s_nop 1
	v_cndmask_b32_e64 v179, v179, v181, s[0:1]
	v_mul_f32_e32 v180, 0x37800000, v179
	v_cndmask_b32_e32 v179, v179, v180, vcc
	v_cmp_class_f32_e32 vcc, v176, v203
	s_nop 1
	v_cndmask_b32_e32 v176, v179, v176, vcc
	v_div_scale_f32 v179, s[0:1], v176, v176, 1.0
	v_rcp_f32_e32 v180, v179
	v_div_scale_f32 v181, vcc, 1.0, v176, 1.0
	v_fma_f32 v182, -v179, v180, 1.0
	v_fmac_f32_e32 v180, v182, v180
	v_mul_f32_e32 v182, v181, v180
	v_fma_f32 v183, -v179, v182, v181
	v_fmac_f32_e32 v182, v183, v180
	v_fma_f32 v179, -v179, v182, v181
	v_div_fmas_f32 v179, v179, v180, v182
	v_div_fixup_f32 v206, v179, v176, 1.0
	v_pk_mul_f32 v[112:113], v[112:113], v[206:207] op_sel_hi:[1,0]
	v_pk_mul_f32 v[114:115], v[114:115], v[206:207] op_sel_hi:[1,0]
	v_pk_mul_f32 v[112:113], v[64:65], v[112:113]
	v_pk_mul_f32 v[114:115], v[66:67], v[114:115]
	v_pk_fma_f32 v[112:113], v[80:81], v[112:113], v[96:97]
	v_pk_fma_f32 v[114:115], v[82:83], v[114:115], v[98:99]
	v_cvt_pk_bf16_f32 v184, v112, v113
	v_cvt_pk_bf16_f32 v185, v114, v115
	global_store_dwordx2 v34, v[184:185], s[16:17]
	v_pk_mul_f32 v[116:117], v[116:117], v[206:207] op_sel_hi:[1,0]
	v_pk_mul_f32 v[118:119], v[118:119], v[206:207] op_sel_hi:[1,0]
	v_pk_mul_f32 v[116:117], v[68:69], v[116:117]
	v_pk_mul_f32 v[118:119], v[70:71], v[118:119]
	v_pk_fma_f32 v[116:117], v[84:85], v[116:117], v[100:101]
	v_pk_fma_f32 v[118:119], v[86:87], v[118:119], v[102:103]
	v_cvt_pk_bf16_f32 v186, v116, v117
	v_cvt_pk_bf16_f32 v187, v118, v119
	global_store_dwordx2 v34, v[186:187], s[16:17] offset:512
	v_pk_mul_f32 v[120:121], v[120:121], v[206:207] op_sel_hi:[1,0]
	v_pk_mul_f32 v[122:123], v[122:123], v[206:207] op_sel_hi:[1,0]
	v_pk_mul_f32 v[120:121], v[72:73], v[120:121]
	v_pk_mul_f32 v[122:123], v[74:75], v[122:123]
	v_pk_fma_f32 v[120:121], v[88:89], v[120:121], v[104:105]
	v_pk_fma_f32 v[122:123], v[90:91], v[122:123], v[106:107]
	v_cvt_pk_bf16_f32 v188, v120, v121
	v_cvt_pk_bf16_f32 v189, v122, v123
	global_store_dwordx2 v34, v[188:189], s[16:17] offset:1024
	v_pk_mul_f32 v[124:125], v[124:125], v[206:207] op_sel_hi:[1,0]
	v_pk_mul_f32 v[126:127], v[126:127], v[206:207] op_sel_hi:[1,0]
	v_pk_mul_f32 v[124:125], v[76:77], v[124:125]
	v_pk_mul_f32 v[126:127], v[78:79], v[126:127]
	v_pk_fma_f32 v[124:125], v[92:93], v[124:125], v[108:109]
	v_pk_fma_f32 v[126:127], v[94:95], v[126:127], v[110:111]
	v_cvt_pk_bf16_f32 v190, v124, v125
	v_cvt_pk_bf16_f32 v191, v126, v127
	global_store_dwordx2 v34, v[190:191], s[16:17] offset:1536
	s_add_u32 s16, s16, 0x100000
	s_addc_u32 s17, s17, 0
	global_load_dwordx4 v[112:115], v200, s[14:15]
	global_load_dwordx4 v[116:119], v200, s[14:15] offset:1024
	global_load_dwordx4 v[120:123], v200, s[14:15] offset:2048
	global_load_dwordx4 v[124:127], v200, s[14:15] offset:3072
	s_add_u32 s14, s14, 0x200000
	s_addc_u32 s15, s15, 0
	s_waitcnt vmcnt(24)
	v_mul_f32_e32 v177, v128, v128
	v_mul_f32_e32 v178, v130, v130
	v_fmac_f32_e32 v177, v129, v129
	v_fmac_f32_e32 v178, v131, v131
	v_add_f32_e32 v176, v177, v178
	v_mul_f32_e32 v177, v132, v132
	v_mul_f32_e32 v178, v134, v134
	v_fmac_f32_e32 v177, v133, v133
	v_fmac_f32_e32 v178, v135, v135
	v_add_f32_e32 v177, v177, v178
	v_add_f32_e32 v176, v176, v177
	v_mul_f32_e32 v177, v136, v136
	v_mul_f32_e32 v178, v138, v138
	v_fmac_f32_e32 v177, v137, v137
	v_fmac_f32_e32 v178, v139, v139
	v_add_f32_e32 v177, v177, v178
	v_add_f32_e32 v176, v176, v177
	v_mul_f32_e32 v177, v140, v140
	v_mul_f32_e32 v178, v142, v142
	v_fmac_f32_e32 v177, v141, v141
	v_fmac_f32_e32 v178, v143, v143
	v_add_f32_e32 v177, v177, v178
	v_add_f32_e32 v176, v176, v177
	s_nop 1
	v_add_f32_dpp v176, v176, v176 quad_perm:[1,0,3,2] row_mask:0xf bank_mask:0xf
	s_nop 1
	v_add_f32_dpp v176, v176, v176 quad_perm:[2,3,0,1] row_mask:0xf bank_mask:0xf
	s_nop 1
	v_add_f32_dpp v176, v176, v176 row_half_mirror row_mask:0xf bank_mask:0xf
	s_nop 1
	v_add_f32_dpp v176, v176, v176 row_mirror row_mask:0xf bank_mask:0xf
	ds_bpermute_b32 v177, v201, v176
	s_waitcnt lgkmcnt(0)
	v_add_f32_e32 v176, v176, v177
	ds_bpermute_b32 v177, v202, v176
	s_waitcnt lgkmcnt(0)
; __device__ __forceinline__ unsigned cvt_pk_bf16(float lo, float hi) { unsigned r; asm volatile("v_cvt_pk_bf16_f32 %0, %1, %2" : "=v"(r) : "v"(lo), "v"(hi)); return r; }
; __device__ __forceinline__ void p1_rows(const Args& A, int lane, int wave) {
;     ...
;         if (m + NGW < M) {
; #pragma unroll
;             for (int j = 0; j < 4; ++j) nx[j] = ((const f32x4*)(A.x + (size_t)(m + NGW) * DM) + lane)[64 * j]; }
; #pragma unroll
;         for (int j = 0; j < 4; ++j) s += (v[j][0] * v[j][0] + v[j][1] * v[j][1]) + (v[j][2] * v[j][2] + v[j][3] * v[j][3]);
;         const float rstd = 1.0f / sqrtf(wave_sum(s) * (1.0f / DM) + RMS_EPS);
;         u32x2* o8 = (u32x2*)(HB + (size_t)m * DM) + lane;
; #pragma unroll
;         for (int j = 0; j < 4; ++j) { const int c = 4 * lane + 256 * j;
;             const f32x4 g = *(const f32x4*)(A.g_ffn1 + c), sc = *(const f32x4*)(mods + (size_t)b * NMODC + MOD_SC1 * DM + c), sh = *(const f32x4*)(mods + (size_t)b * NMODC + MOD_SH1 * DM + c);
;             const f32x4 h = (v[j] * rstd) * g * (sc + 1.0f) + sh;
;             u32x2 w; w.x = pg8::cvt_pk_bf16(h[0], h[1]); w.y = pg8::cvt_pk_bf16(h[2], h[3]); o8[64 * j] = w; }
	v_add_f32_e32 v176, v176, v177
	v_fmamk_f32 v176, v176, 0x3a800000, v204
	v_mul_f32_e32 v179, 0x4f800000, v176
	v_cmp_gt_f32_e32 vcc, s20, v176
	s_nop 1
	v_cndmask_b32_e32 v176, v176, v179, vcc
	v_sqrt_f32_e32 v179, v176
	s_nop 0
	v_add_u32_e32 v180, -1, v179
	v_add_u32_e32 v181, 1, v179
	v_fma_f32 v182, -v180, v179, v176
	v_fma_f32 v183, -v181, v179, v176
	v_cmp_ge_f32_e64 s[0:1], 0, v182
	s_nop 1
	v_cndmask_b32_e64 v179, v179, v180, s[0:1]
	v_cmp_lt_f32_e64 s[0:1], 0, v183
	s_nop 1
	v_cndmask_b32_e64 v179, v179, v181, s[0:1]
	v_mul_f32_e32 v180, 0x37800000, v179
	v_cndmask_b32_e32 v179, v179, v180, vcc
	v_cmp_class_f32_e32 vcc, v176, v203
	s_nop 1
	v_cndmask_b32_e32 v176, v179, v176, vcc
	v_div_scale_f32 v179, s[0:1], v176, v176, 1.0
	v_rcp_f32_e32 v180, v179
	v_div_scale_f32 v181, vcc, 1.0, v176, 1.0
	v_fma_f32 v182, -v179, v180, 1.0
	v_fmac_f32_e32 v180, v182, v180
	v_mul_f32_e32 v182, v181, v180
	v_fma_f32 v183, -v179, v182, v181
	v_fmac_f32_e32 v182, v183, v180
	v_fma_f32 v179, -v179, v182, v181
	v_div_fmas_f32 v179, v179, v180, v182
	v_div_fixup_f32 v206, v179, v176, 1.0
	v_pk_mul_f32 v[128:129], v[128:129], v[206:207] op_sel_hi:[1,0]
	v_pk_mul_f32 v[130:131], v[130:131], v[206:207] op_sel_hi:[1,0]
	v_pk_mul_f32 v[128:129], v[64:65], v[128:129]
	v_pk_mul_f32 v[130:131], v[66:67], v[130:131]
	v_pk_fma_f32 v[128:129], v[80:81], v[128:129], v[96:97]
	v_pk_fma_f32 v[130:131], v[82:83], v[130:131], v[98:99]
	v_cvt_pk_bf16_f32 v192, v128, v129
	v_cvt_pk_bf16_f32 v193, v130, v131
	global_store_dwordx2 v34, v[192:193], s[16:17]
	v_pk_mul_f32 v[132:133], v[132:133], v[206:207] op_sel_hi:[1,0]
	v_pk_mul_f32 v[134:135], v[134:135], v[206:207] op_sel_hi:[1,0]
	v_pk_mul_f32 v[132:133], v[68:69], v[132:133]
	v_pk_mul_f32 v[134:135], v[70:71], v[134:135]
	v_pk_fma_f32 v[132:133], v[84:85], v[132:133], v[100:101]
	v_pk_fma_f32 v[134:135], v[86:87], v[134:135], v[102:103]
	v_cvt_pk_bf16_f32 v194, v132, v133
	v_cvt_pk_bf16_f32 v195, v134, v135
	global_store_dwordx2 v34, v[194:195], s[16:17] offset:512
	v_pk_mul_f32 v[136:137], v[136:137], v[206:207] op_sel_hi:[1,0]
	v_pk_mul_f32 v[138:139], v[138:139], v[206:207] op_sel_hi:[1,0]
	v_pk_mul_f32 v[136:137], v[72:73], v[136:137]
	v_pk_mul_f32 v[138:139], v[74:75], v[138:139]
	v_pk_fma_f32 v[136:137], v[88:89], v[136:137], v[104:105]
	v_pk_fma_f32 v[138:139], v[90:91], v[138:139], v[106:107]
	v_cvt_pk_bf16_f32 v196, v136, v137
	v_cvt_pk_bf16_f32 v197, v138, v139
	global_store_dwordx2 v34, v[196:197], s[16:17] offset:1024
	v_pk_mul_f32 v[140:141], v[140:141], v[206:207] op_sel_hi:[1,0]
	v_pk_mul_f32 v[142:143], v[142:143], v[206:207] op_sel_hi:[1,0]
	v_pk_mul_f32 v[140:141], v[76:77], v[140:141]
	v_pk_mul_f32 v[142:143], v[78:79], v[142:143]
	v_pk_fma_f32 v[140:141], v[92:93], v[140:141], v[108:109]
	v_pk_fma_f32 v[142:143], v[94:95], v[142:143], v[110:111]
	v_cvt_pk_bf16_f32 v198, v140, v141
	v_cvt_pk_bf16_f32 v199, v142, v143
	global_store_dwordx2 v34, v[198:199], s[16:17] offset:1536
	s_add_u32 s16, s16, 0x100000
	s_addc_u32 s17, s17, 0
	global_load_dwordx4 v[128:131], v200, s[14:15]
	global_load_dwordx4 v[132:135], v200, s[14:15] offset:1024
	global_load_dwordx4 v[136:139], v200, s[14:15] offset:2048
	global_load_dwordx4 v[140:143], v200, s[14:15] offset:3072
	s_add_u32 s14, s14, 0x200000
	s_addc_u32 s15, s15, 0
	s_waitcnt vmcnt(24)
	v_mul_f32_e32 v177, v144, v144
	v_mul_f32_e32 v178, v146, v146
	v_fmac_f32_e32 v177, v145, v145
	v_fmac_f32_e32 v178, v147, v147
	v_add_f32_e32 v176, v177, v178
	v_mul_f32_e32 v177, v148, v148
	v_mul_f32_e32 v178, v150, v150
	v_fmac_f32_e32 v177, v149, v149
	v_fmac_f32_e32 v178, v151, v151
	v_add_f32_e32 v177, v177, v178
	v_add_f32_e32 v176, v176, v177
	v_mul_f32_e32 v177, v152, v152
	v_mul_f32_e32 v178, v154, v154
	v_fmac_f32_e32 v177, v153, v153
	v_fmac_f32_e32 v178, v155, v155
	v_add_f32_e32 v177, v177, v178
	v_add_f32_e32 v176, v176, v177
	v_mul_f32_e32 v177, v156, v156
	v_mul_f32_e32 v178, v158, v158
	v_fmac_f32_e32 v177, v157, v157
	v_fmac_f32_e32 v178, v159, v159
	v_add_f32_e32 v177, v177, v178
	v_add_f32_e32 v176, v176, v177
	s_nop 1
	v_add_f32_dpp v176, v176, v176 quad_perm:[1,0,3,2] row_mask:0xf bank_mask:0xf
	s_nop 1
	v_add_f32_dpp v176, v176, v176 quad_perm:[2,3,0,1] row_mask:0xf bank_mask:0xf
	s_nop 1
	v_add_f32_dpp v176, v176, v176 row_half_mirror row_mask:0xf bank_mask:0xf
	s_nop 1
	v_add_f32_dpp v176, v176, v176 row_mirror row_mask:0xf bank_mask:0xf
	ds_bpermute_b32 v177, v201, v176
	s_waitcnt lgkmcnt(0)
	v_add_f32_e32 v176, v176, v177
	ds_bpermute_b32 v177, v202, v176
	s_waitcnt lgkmcnt(0)
; __device__ __forceinline__ unsigned cvt_pk_bf16(float lo, float hi) { unsigned r; asm volatile("v_cvt_pk_bf16_f32 %0, %1, %2" : "=v"(r) : "v"(lo), "v"(hi)); return r; }
; __device__ __forceinline__ void p1_rows(const Args& A, int lane, int wave) {
;     ...
;         if (m + NGW < M) {
; #pragma unroll
;             for (int j = 0; j < 4; ++j) nx[j] = ((const f32x4*)(A.x + (size_t)(m + NGW) * DM) + lane)[64 * j]; }
; #pragma unroll
;         for (int j = 0; j < 4; ++j) s += (v[j][0] * v[j][0] + v[j][1] * v[j][1]) + (v[j][2] * v[j][2] + v[j][3] * v[j][3]);
;         const float rstd = 1.0f / sqrtf(wave_sum(s) * (1.0f / DM) + RMS_EPS);
;         u32x2* o8 = (u32x2*)(HB + (size_t)m * DM) + lane;
; #pragma unroll
;         for (int j = 0; j < 4; ++j) { const int c = 4 * lane + 256 * j;
;             const f32x4 g = *(const f32x4*)(A.g_ffn1 + c), sc = *(const f32x4*)(mods + (size_t)b * NMODC + MOD_SC1 * DM + c), sh = *(const f32x4*)(mods + (size_t)b * NMODC + MOD_SH1 * DM + c);
;             const f32x4 h = (v[j] * rstd) * g * (sc + 1.0f) + sh;
;             u32x2 w; w.x = pg8::cvt_pk_bf16(h[0], h[1]); w.y = pg8::cvt_pk_bf16(h[2], h[3]); o8[64 * j] = w; }
	v_add_f32_e32 v176, v176, v177
	v_fmamk_f32 v176, v176, 0x3a800000, v204
	v_mul_f32_e32 v179, 0x4f800000, v176
	v_cmp_gt_f32_e32 vcc, s20, v176
	s_nop 1
	v_cndmask_b32_e32 v176, v176, v179, vcc
	v_sqrt_f32_e32 v179, v176
	s_nop 0
	v_add_u32_e32 v180, -1, v179
	v_add_u32_e32 v181, 1, v179
	v_fma_f32 v182, -v180, v179, v176
	v_fma_f32 v183, -v181, v179, v176
	v_cmp_ge_f32_e64 s[0:1], 0, v182
	s_nop 1
	v_cndmask_b32_e64 v179, v179, v180, s[0:1]
	v_cmp_lt_f32_e64 s[0:1], 0, v183
	s_nop 1
	v_cndmask_b32_e64 v179, v179, v181, s[0:1]
	v_mul_f32_e32 v180, 0x37800000, v179
	v_cndmask_b32_e32 v179, v179, v180, vcc
	v_cmp_class_f32_e32 vcc, v176, v203
	s_nop 1
	v_cndmask_b32_e32 v176, v179, v176, vcc
	v_div_scale_f32 v179, s[0:1], v176, v176, 1.0
	v_rcp_f32_e32 v180, v179
	v_div_scale_f32 v181, vcc, 1.0, v176, 1.0
	v_fma_f32 v182, -v179, v180, 1.0
	v_fmac_f32_e32 v180, v182, v180
	v_mul_f32_e32 v182, v181, v180
	v_fma_f32 v183, -v179, v182, v181
	v_fmac_f32_e32 v182, v183, v180
	v_fma_f32 v179, -v179, v182, v181
	v_div_fmas_f32 v179, v179, v180, v182
	v_div_fixup_f32 v206, v179, v176, 1.0
	v_pk_mul_f32 v[144:145], v[144:145], v[206:207] op_sel_hi:[1,0]
	v_pk_mul_f32 v[146:147], v[146:147], v[206:207] op_sel_hi:[1,0]
	v_pk_mul_f32 v[144:145], v[64:65], v[144:145]
	v_pk_mul_f32 v[146:147], v[66:67], v[146:147]
	v_pk_fma_f32 v[144:145], v[80:81], v[144:145], v[96:97]
	v_pk_fma_f32 v[146:147], v[82:83], v[146:147], v[98:99]
	v_cvt_pk_bf16_f32 v184, v144, v145
	v_cvt_pk_bf16_f32 v185, v146, v147
	global_store_dwordx2 v34, v[184:185], s[16:17]
	v_pk_mul_f32 v[148:149], v[148:149], v[206:207] op_sel_hi:[1,0]
	v_pk_mul_f32 v[150:151], v[150:151], v[206:207] op_sel_hi:[1,0]
	v_pk_mul_f32 v[148:149], v[68:69], v[148:149]
	v_pk_mul_f32 v[150:151], v[70:71], v[150:151]
	v_pk_fma_f32 v[148:149], v[84:85], v[148:149], v[100:101]
	v_pk_fma_f32 v[150:151], v[86:87], v[150:151], v[102:103]
	v_cvt_pk_bf16_f32 v186, v148, v149
	v_cvt_pk_bf16_f32 v187, v150, v151
	global_store_dwordx2 v34, v[186:187], s[16:17] offset:512
	v_pk_mul_f32 v[152:153], v[152:153], v[206:207] op_sel_hi:[1,0]
	v_pk_mul_f32 v[154:155], v[154:155], v[206:207] op_sel_hi:[1,0]
	v_pk_mul_f32 v[152:153], v[72:73], v[152:153]
	v_pk_mul_f32 v[154:155], v[74:75], v[154:155]
	v_pk_fma_f32 v[152:153], v[88:89], v[152:153], v[104:105]
	v_pk_fma_f32 v[154:155], v[90:91], v[154:155], v[106:107]
	v_cvt_pk_bf16_f32 v188, v152, v153
	v_cvt_pk_bf16_f32 v189, v154, v155
	global_store_dwordx2 v34, v[188:189], s[16:17] offset:1024
	v_pk_mul_f32 v[156:157], v[156:157], v[206:207] op_sel_hi:[1,0]
	v_pk_mul_f32 v[158:159], v[158:159], v[206:207] op_sel_hi:[1,0]
	v_pk_mul_f32 v[156:157], v[76:77], v[156:157]
	v_pk_mul_f32 v[158:159], v[78:79], v[158:159]
	v_pk_fma_f32 v[156:157], v[92:93], v[156:157], v[108:109]
	v_pk_fma_f32 v[158:159], v[94:95], v[158:159], v[110:111]
	v_cvt_pk_bf16_f32 v190, v156, v157
	v_cvt_pk_bf16_f32 v191, v158, v159
	global_store_dwordx2 v34, v[190:191], s[16:17] offset:1536
	s_add_u32 s16, s16, 0x100000
	s_addc_u32 s17, s17, 0
	global_load_dwordx4 v[144:147], v200, s[14:15]
	global_load_dwordx4 v[148:151], v200, s[14:15] offset:1024
	global_load_dwordx4 v[152:155], v200, s[14:15] offset:2048
	global_load_dwordx4 v[156:159], v200, s[14:15] offset:3072
	s_add_u32 s14, s14, 0x200000
	s_addc_u32 s15, s15, 0
	s_waitcnt vmcnt(24)
	v_mul_f32_e32 v177, v160, v160
	v_mul_f32_e32 v178, v162, v162
	v_fmac_f32_e32 v177, v161, v161
	v_fmac_f32_e32 v178, v163, v163
	v_add_f32_e32 v176, v177, v178
	v_mul_f32_e32 v177, v164, v164
	v_mul_f32_e32 v178, v166, v166
	v_fmac_f32_e32 v177, v165, v165
	v_fmac_f32_e32 v178, v167, v167
	v_add_f32_e32 v177, v177, v178
	v_add_f32_e32 v176, v176, v177
	v_mul_f32_e32 v177, v168, v168
	v_mul_f32_e32 v178, v170, v170
	v_fmac_f32_e32 v177, v169, v169
	v_fmac_f32_e32 v178, v171, v171
	v_add_f32_e32 v177, v177, v178
	v_add_f32_e32 v176, v176, v177
	v_mul_f32_e32 v177, v172, v172
	v_mul_f32_e32 v178, v174, v174
	v_fmac_f32_e32 v177, v173, v173
	v_fmac_f32_e32 v178, v175, v175
	v_add_f32_e32 v177, v177, v178
	v_add_f32_e32 v176, v176, v177
	s_nop 1
	v_add_f32_dpp v176, v176, v176 quad_perm:[1,0,3,2] row_mask:0xf bank_mask:0xf
	s_nop 1
	v_add_f32_dpp v176, v176, v176 quad_perm:[2,3,0,1] row_mask:0xf bank_mask:0xf
	s_nop 1
	v_add_f32_dpp v176, v176, v176 row_half_mirror row_mask:0xf bank_mask:0xf
	s_nop 1
	v_add_f32_dpp v176, v176, v176 row_mirror row_mask:0xf bank_mask:0xf
	ds_bpermute_b32 v177, v201, v176
	s_waitcnt lgkmcnt(0)
	v_add_f32_e32 v176, v176, v177
	ds_bpermute_b32 v177, v202, v176
	s_waitcnt lgkmcnt(0)
; __device__ __forceinline__ unsigned cvt_pk_bf16(float lo, float hi) { unsigned r; asm volatile("v_cvt_pk_bf16_f32 %0, %1, %2" : "=v"(r) : "v"(lo), "v"(hi)); return r; }
; __device__ __forceinline__ void p1_rows(const Args& A, int lane, int wave) {
;     ...
;         if (m + NGW < M) {
; #pragma unroll
;             for (int j = 0; j < 4; ++j) nx[j] = ((const f32x4*)(A.x + (size_t)(m + NGW) * DM) + lane)[64 * j]; }
; #pragma unroll
;         for (int j = 0; j < 4; ++j) s += (v[j][0] * v[j][0] + v[j][1] * v[j][1]) + (v[j][2] * v[j][2] + v[j][3] * v[j][3]);
;         const float rstd = 1.0f / sqrtf(wave_sum(s) * (1.0f / DM) + RMS_EPS);
;         u32x2* o8 = (u32x2*)(HB + (size_t)m * DM) + lane;
; #pragma unroll
;         for (int j = 0; j < 4; ++j) { const int c = 4 * lane + 256 * j;
;             const f32x4 g = *(const f32x4*)(A.g_ffn1 + c), sc = *(const f32x4*)(mods + (size_t)b * NMODC + MOD_SC1 * DM + c), sh = *(const f32x4*)(mods + (size_t)b * NMODC + MOD_SH1 * DM + c);
;             const f32x4 h = (v[j] * rstd) * g * (sc + 1.0f) + sh;
;             u32x2 w; w.x = pg8::cvt_pk_bf16(h[0], h[1]); w.y = pg8::cvt_pk_bf16(h[2], h[3]); o8[64 * j] = w; }
	v_add_f32_e32 v176, v176, v177
	v_fmamk_f32 v176, v176, 0x3a800000, v204
	v_mul_f32_e32 v179, 0x4f800000, v176
	v_cmp_gt_f32_e32 vcc, s20, v176
	s_nop 1
	v_cndmask_b32_e32 v176, v176, v179, vcc
	v_sqrt_f32_e32 v179, v176
	s_nop 0
	v_add_u32_e32 v180, -1, v179
	v_add_u32_e32 v181, 1, v179
	v_fma_f32 v182, -v180, v179, v176
	v_fma_f32 v183, -v181, v179, v176
	v_cmp_ge_f32_e64 s[0:1], 0, v182
	s_nop 1
	v_cndmask_b32_e64 v179, v179, v180, s[0:1]
	v_cmp_lt_f32_e64 s[0:1], 0, v183
	s_nop 1
	v_cndmask_b32_e64 v179, v179, v181, s[0:1]
	v_mul_f32_e32 v180, 0x37800000, v179
	v_cndmask_b32_e32 v179, v179, v180, vcc
	v_cmp_class_f32_e32 vcc, v176, v203
	s_nop 1
	v_cndmask_b32_e32 v176, v179, v176, vcc
	v_div_scale_f32 v179, s[0:1], v176, v176, 1.0
	v_rcp_f32_e32 v180, v179
	v_div_scale_f32 v181, vcc, 1.0, v176, 1.0
	v_fma_f32 v182, -v179, v180, 1.0
	v_fmac_f32_e32 v180, v182, v180
	v_mul_f32_e32 v182, v181, v180
	v_fma_f32 v183, -v179, v182, v181
	v_fmac_f32_e32 v182, v183, v180
	v_fma_f32 v179, -v179, v182, v181
	v_div_fmas_f32 v179, v179, v180, v182
	v_div_fixup_f32 v206, v179, v176, 1.0
	v_pk_mul_f32 v[160:161], v[160:161], v[206:207] op_sel_hi:[1,0]
	v_pk_mul_f32 v[162:163], v[162:163], v[206:207] op_sel_hi:[1,0]
	v_pk_mul_f32 v[160:161], v[64:65], v[160:161]
	v_pk_mul_f32 v[162:163], v[66:67], v[162:163]
	v_pk_fma_f32 v[160:161], v[80:81], v[160:161], v[96:97]
	v_pk_fma_f32 v[162:163], v[82:83], v[162:163], v[98:99]
	v_cvt_pk_bf16_f32 v192, v160, v161
	v_cvt_pk_bf16_f32 v193, v162, v163
	global_store_dwordx2 v34, v[192:193], s[16:17]
	v_pk_mul_f32 v[164:165], v[164:165], v[206:207] op_sel_hi:[1,0]
	v_pk_mul_f32 v[166:167], v[166:167], v[206:207] op_sel_hi:[1,0]
	v_pk_mul_f32 v[164:165], v[68:69], v[164:165]
	v_pk_mul_f32 v[166:167], v[70:71], v[166:167]
	v_pk_fma_f32 v[164:165], v[84:85], v[164:165], v[100:101]
	v_pk_fma_f32 v[166:167], v[86:87], v[166:167], v[102:103]
	v_cvt_pk_bf16_f32 v194, v164, v165
	v_cvt_pk_bf16_f32 v195, v166, v167
	global_store_dwordx2 v34, v[194:195], s[16:17] offset:512
	v_pk_mul_f32 v[168:169], v[168:169], v[206:207] op_sel_hi:[1,0]
	v_pk_mul_f32 v[170:171], v[170:171], v[206:207] op_sel_hi:[1,0]
	v_pk_mul_f32 v[168:169], v[72:73], v[168:169]
	v_pk_mul_f32 v[170:171], v[74:75], v[170:171]
	v_pk_fma_f32 v[168:169], v[88:89], v[168:169], v[104:105]
	v_pk_fma_f32 v[170:171], v[90:91], v[170:171], v[106:107]
	v_cvt_pk_bf16_f32 v196, v168, v169
	v_cvt_pk_bf16_f32 v197, v170, v171
	global_store_dwordx2 v34, v[196:197], s[16:17] offset:1024
	v_pk_mul_f32 v[172:173], v[172:173], v[206:207] op_sel_hi:[1,0]
	v_pk_mul_f32 v[174:175], v[174:175], v[206:207] op_sel_hi:[1,0]
	v_pk_mul_f32 v[172:173], v[76:77], v[172:173]
	v_pk_mul_f32 v[174:175], v[78:79], v[174:175]
	v_pk_fma_f32 v[172:173], v[92:93], v[172:173], v[108:109]
	v_pk_fma_f32 v[174:175], v[94:95], v[174:175], v[110:111]
	v_cvt_pk_bf16_f32 v198, v172, v173
	v_cvt_pk_bf16_f32 v199, v174, v175
	global_store_dwordx2 v34, v[198:199], s[16:17] offset:1536
	s_add_u32 s16, s16, 0x100000
	s_addc_u32 s17, s17, 0
	global_load_dwordx4 v[160:163], v200, s[14:15]
	global_load_dwordx4 v[164:167], v200, s[14:15] offset:1024
	global_load_dwordx4 v[168:171], v200, s[14:15] offset:2048
	global_load_dwordx4 v[172:175], v200, s[14:15] offset:3072
	s_add_u32 s14, s14, 0x200000
	s_addc_u32 s15, s15, 0
	s_waitcnt vmcnt(24)
	v_mul_f32_e32 v177, v112, v112
	v_mul_f32_e32 v178, v114, v114
	v_fmac_f32_e32 v177, v113, v113
	v_fmac_f32_e32 v178, v115, v115
	v_add_f32_e32 v176, v177, v178
	v_mul_f32_e32 v177, v116, v116
	v_mul_f32_e32 v178, v118, v118
	v_fmac_f32_e32 v177, v117, v117
	v_fmac_f32_e32 v178, v119, v119
	v_add_f32_e32 v177, v177, v178
	v_add_f32_e32 v176, v176, v177
	v_mul_f32_e32 v177, v120, v120
	v_mul_f32_e32 v178, v122, v122
	v_fmac_f32_e32 v177, v121, v121
	v_fmac_f32_e32 v178, v123, v123
	v_add_f32_e32 v177, v177, v178
	v_add_f32_e32 v176, v176, v177
	v_mul_f32_e32 v177, v124, v124
	v_mul_f32_e32 v178, v126, v126
	v_fmac_f32_e32 v177, v125, v125
	v_fmac_f32_e32 v178, v127, v127
	v_add_f32_e32 v177, v177, v178
	v_add_f32_e32 v176, v176, v177
	s_nop 1
	v_add_f32_dpp v176, v176, v176 quad_perm:[1,0,3,2] row_mask:0xf bank_mask:0xf
	s_nop 1
	v_add_f32_dpp v176, v176, v176 quad_perm:[2,3,0,1] row_mask:0xf bank_mask:0xf
	s_nop 1
	v_add_f32_dpp v176, v176, v176 row_half_mirror row_mask:0xf bank_mask:0xf
	s_nop 1
	v_add_f32_dpp v176, v176, v176 row_mirror row_mask:0xf bank_mask:0xf
	ds_bpermute_b32 v177, v201, v176
	s_waitcnt lgkmcnt(0)
	v_add_f32_e32 v176, v176, v177
	ds_bpermute_b32 v177, v202, v176
	s_waitcnt lgkmcnt(0)
; __device__ __forceinline__ unsigned cvt_pk_bf16(float lo, float hi) { unsigned r; asm volatile("v_cvt_pk_bf16_f32 %0, %1, %2" : "=v"(r) : "v"(lo), "v"(hi)); return r; }
; __device__ __forceinline__ void p1_rows(const Args& A, int lane, int wave) {
;     ...
;         if (m + NGW < M) {
; #pragma unroll
;             for (int j = 0; j < 4; ++j) nx[j] = ((const f32x4*)(A.x + (size_t)(m + NGW) * DM) + lane)[64 * j]; }
; #pragma unroll
;         for (int j = 0; j < 4; ++j) s += (v[j][0] * v[j][0] + v[j][1] * v[j][1]) + (v[j][2] * v[j][2] + v[j][3] * v[j][3]);
;         const float rstd = 1.0f / sqrtf(wave_sum(s) * (1.0f / DM) + RMS_EPS);
;         u32x2* o8 = (u32x2*)(HB + (size_t)m * DM) + lane;
; #pragma unroll
;         for (int j = 0; j < 4; ++j) { const int c = 4 * lane + 256 * j;
;             const f32x4 g = *(const f32x4*)(A.g_ffn1 + c), sc = *(const f32x4*)(mods + (size_t)b * NMODC + MOD_SC1 * DM + c), sh = *(const f32x4*)(mods + (size_t)b * NMODC + MOD_SH1 * DM + c);
;             const f32x4 h = (v[j] * rstd) * g * (sc + 1.0f) + sh;
;             u32x2 w; w.x = pg8::cvt_pk_bf16(h[0], h[1]); w.y = pg8::cvt_pk_bf16(h[2], h[3]); o8[64 * j] = w; }
	v_add_f32_e32 v176, v176, v177
	v_fmamk_f32 v176, v176, 0x3a800000, v204
	v_mul_f32_e32 v179, 0x4f800000, v176
	v_cmp_gt_f32_e32 vcc, s20, v176
	s_nop 1
	v_cndmask_b32_e32 v176, v176, v179, vcc
	v_sqrt_f32_e32 v179, v176
	s_nop 0
	v_add_u32_e32 v180, -1, v179
	v_add_u32_e32 v181, 1, v179
	v_fma_f32 v182, -v180, v179, v176
	v_fma_f32 v183, -v181, v179, v176
	v_cmp_ge_f32_e64 s[0:1], 0, v182
	s_nop 1
	v_cndmask_b32_e64 v179, v179, v180, s[0:1]
	v_cmp_lt_f32_e64 s[0:1], 0, v183
	s_nop 1
	v_cndmask_b32_e64 v179, v179, v181, s[0:1]
	v_mul_f32_e32 v180, 0x37800000, v179
	v_cndmask_b32_e32 v179, v179, v180, vcc
	v_cmp_class_f32_e32 vcc, v176, v203
	s_nop 1
	v_cndmask_b32_e32 v176, v179, v176, vcc
	v_div_scale_f32 v179, s[0:1], v176, v176, 1.0
	v_rcp_f32_e32 v180, v179
	v_div_scale_f32 v181, vcc, 1.0, v176, 1.0
	v_fma_f32 v182, -v179, v180, 1.0
	v_fmac_f32_e32 v180, v182, v180
	v_mul_f32_e32 v182, v181, v180
	v_fma_f32 v183, -v179, v182, v181
	v_fmac_f32_e32 v182, v183, v180
	v_fma_f32 v179, -v179, v182, v181
	v_div_fmas_f32 v179, v179, v180, v182
	v_div_fixup_f32 v206, v179, v176, 1.0
	v_pk_mul_f32 v[112:113], v[112:113], v[206:207] op_sel_hi:[1,0]
	v_pk_mul_f32 v[114:115], v[114:115], v[206:207] op_sel_hi:[1,0]
	v_pk_mul_f32 v[112:113], v[64:65], v[112:113]
	v_pk_mul_f32 v[114:115], v[66:67], v[114:115]
	v_pk_fma_f32 v[112:113], v[80:81], v[112:113], v[96:97]
	v_pk_fma_f32 v[114:115], v[82:83], v[114:115], v[98:99]
	v_cvt_pk_bf16_f32 v184, v112, v113
	v_cvt_pk_bf16_f32 v185, v114, v115
	global_store_dwordx2 v34, v[184:185], s[16:17]
	v_pk_mul_f32 v[116:117], v[116:117], v[206:207] op_sel_hi:[1,0]
	v_pk_mul_f32 v[118:119], v[118:119], v[206:207] op_sel_hi:[1,0]
	v_pk_mul_f32 v[116:117], v[68:69], v[116:117]
	v_pk_mul_f32 v[118:119], v[70:71], v[118:119]
	v_pk_fma_f32 v[116:117], v[84:85], v[116:117], v[100:101]
	v_pk_fma_f32 v[118:119], v[86:87], v[118:119], v[102:103]
	v_cvt_pk_bf16_f32 v186, v116, v117
	v_cvt_pk_bf16_f32 v187, v118, v119
	global_store_dwordx2 v34, v[186:187], s[16:17] offset:512
	v_pk_mul_f32 v[120:121], v[120:121], v[206:207] op_sel_hi:[1,0]
	v_pk_mul_f32 v[122:123], v[122:123], v[206:207] op_sel_hi:[1,0]
	v_pk_mul_f32 v[120:121], v[72:73], v[120:121]
	v_pk_mul_f32 v[122:123], v[74:75], v[122:123]
	v_pk_fma_f32 v[120:121], v[88:89], v[120:121], v[104:105]
	v_pk_fma_f32 v[122:123], v[90:91], v[122:123], v[106:107]
	v_cvt_pk_bf16_f32 v188, v120, v121
	v_cvt_pk_bf16_f32 v189, v122, v123
	global_store_dwordx2 v34, v[188:189], s[16:17] offset:1024
	v_pk_mul_f32 v[124:125], v[124:125], v[206:207] op_sel_hi:[1,0]
	v_pk_mul_f32 v[126:127], v[126:127], v[206:207] op_sel_hi:[1,0]
	v_pk_mul_f32 v[124:125], v[76:77], v[124:125]
	v_pk_mul_f32 v[126:127], v[78:79], v[126:127]
	v_pk_fma_f32 v[124:125], v[92:93], v[124:125], v[108:109]
	v_pk_fma_f32 v[126:127], v[94:95], v[126:127], v[110:111]
	v_cvt_pk_bf16_f32 v190, v124, v125
	v_cvt_pk_bf16_f32 v191, v126, v127
	global_store_dwordx2 v34, v[190:191], s[16:17] offset:1536
	s_add_u32 s16, s16, 0x100000
	s_addc_u32 s17, s17, 0
	global_load_dwordx4 v[112:115], v200, s[14:15]
	global_load_dwordx4 v[116:119], v200, s[14:15] offset:1024
	global_load_dwordx4 v[120:123], v200, s[14:15] offset:2048
	global_load_dwordx4 v[124:127], v200, s[14:15] offset:3072
	s_add_u32 s14, s14, 0x200000
	s_addc_u32 s15, s15, 0
	s_waitcnt vmcnt(24)
	v_mul_f32_e32 v177, v128, v128
	v_mul_f32_e32 v178, v130, v130
	v_fmac_f32_e32 v177, v129, v129
	v_fmac_f32_e32 v178, v131, v131
	v_add_f32_e32 v176, v177, v178
	v_mul_f32_e32 v177, v132, v132
	v_mul_f32_e32 v178, v134, v134
	v_fmac_f32_e32 v177, v133, v133
	v_fmac_f32_e32 v178, v135, v135
	v_add_f32_e32 v177, v177, v178
	v_add_f32_e32 v176, v176, v177
	v_mul_f32_e32 v177, v136, v136
	v_mul_f32_e32 v178, v138, v138
	v_fmac_f32_e32 v177, v137, v137
	v_fmac_f32_e32 v178, v139, v139
	v_add_f32_e32 v177, v177, v178
	v_add_f32_e32 v176, v176, v177
	v_mul_f32_e32 v177, v140, v140
	v_mul_f32_e32 v178, v142, v142
	v_fmac_f32_e32 v177, v141, v141
	v_fmac_f32_e32 v178, v143, v143
	v_add_f32_e32 v177, v177, v178
	v_add_f32_e32 v176, v176, v177
	s_nop 1
	v_add_f32_dpp v176, v176, v176 quad_perm:[1,0,3,2] row_mask:0xf bank_mask:0xf
	s_nop 1
	v_add_f32_dpp v176, v176, v176 quad_perm:[2,3,0,1] row_mask:0xf bank_mask:0xf
	s_nop 1
	v_add_f32_dpp v176, v176, v176 row_half_mirror row_mask:0xf bank_mask:0xf
	s_nop 1
	v_add_f32_dpp v176, v176, v176 row_mirror row_mask:0xf bank_mask:0xf
	ds_bpermute_b32 v177, v201, v176
	s_waitcnt lgkmcnt(0)
	v_add_f32_e32 v176, v176, v177
	ds_bpermute_b32 v177, v202, v176
	s_waitcnt lgkmcnt(0)
; __device__ __forceinline__ unsigned cvt_pk_bf16(float lo, float hi) { unsigned r; asm volatile("v_cvt_pk_bf16_f32 %0, %1, %2" : "=v"(r) : "v"(lo), "v"(hi)); return r; }
; __device__ __forceinline__ void p1_rows(const Args& A, int lane, int wave) {
;     ...
;         if (m + NGW < M) {
; #pragma unroll
;             for (int j = 0; j < 4; ++j) nx[j] = ((const f32x4*)(A.x + (size_t)(m + NGW) * DM) + lane)[64 * j]; }
; #pragma unroll
;         for (int j = 0; j < 4; ++j) s += (v[j][0] * v[j][0] + v[j][1] * v[j][1]) + (v[j][2] * v[j][2] + v[j][3] * v[j][3]);
;         const float rstd = 1.0f / sqrtf(wave_sum(s) * (1.0f / DM) + RMS_EPS);
;         u32x2* o8 = (u32x2*)(HB + (size_t)m * DM) + lane;
; #pragma unroll
;         for (int j = 0; j < 4; ++j) { const int c = 4 * lane + 256 * j;
;             const f32x4 g = *(const f32x4*)(A.g_ffn1 + c), sc = *(const f32x4*)(mods + (size_t)b * NMODC + MOD_SC1 * DM + c), sh = *(const f32x4*)(mods + (size_t)b * NMODC + MOD_SH1 * DM + c);
;             const f32x4 h = (v[j] * rstd) * g * (sc + 1.0f) + sh;
;             u32x2 w; w.x = pg8::cvt_pk_bf16(h[0], h[1]); w.y = pg8::cvt_pk_bf16(h[2], h[3]); o8[64 * j] = w; }
	v_add_f32_e32 v176, v176, v177
	v_fmamk_f32 v176, v176, 0x3a800000, v204
	v_mul_f32_e32 v179, 0x4f800000, v176
	v_cmp_gt_f32_e32 vcc, s20, v176
	s_nop 1
	v_cndmask_b32_e32 v176, v176, v179, vcc
	v_sqrt_f32_e32 v179, v176
	s_nop 0
	v_add_u32_e32 v180, -1, v179
	v_add_u32_e32 v181, 1, v179
	v_fma_f32 v182, -v180, v179, v176
	v_fma_f32 v183, -v181, v179, v176
	v_cmp_ge_f32_e64 s[0:1], 0, v182
	s_nop 1
	v_cndmask_b32_e64 v179, v179, v180, s[0:1]
	v_cmp_lt_f32_e64 s[0:1], 0, v183
	s_nop 1
	v_cndmask_b32_e64 v179, v179, v181, s[0:1]
	v_mul_f32_e32 v180, 0x37800000, v179
	v_cndmask_b32_e32 v179, v179, v180, vcc
	v_cmp_class_f32_e32 vcc, v176, v203
	s_nop 1
	v_cndmask_b32_e32 v176, v179, v176, vcc
	v_div_scale_f32 v179, s[0:1], v176, v176, 1.0
	v_rcp_f32_e32 v180, v179
	v_div_scale_f32 v181, vcc, 1.0, v176, 1.0
	v_fma_f32 v182, -v179, v180, 1.0
	v_fmac_f32_e32 v180, v182, v180
	v_mul_f32_e32 v182, v181, v180
	v_fma_f32 v183, -v179, v182, v181
	v_fmac_f32_e32 v182, v183, v180
	v_fma_f32 v179, -v179, v182, v181
	v_div_fmas_f32 v179, v179, v180, v182
	v_div_fixup_f32 v206, v179, v176, 1.0
	v_pk_mul_f32 v[128:129], v[128:129], v[206:207] op_sel_hi:[1,0]
	v_pk_mul_f32 v[130:131], v[130:131], v[206:207] op_sel_hi:[1,0]
	v_pk_mul_f32 v[128:129], v[64:65], v[128:129]
	v_pk_mul_f32 v[130:131], v[66:67], v[130:131]
	v_pk_fma_f32 v[128:129], v[80:81], v[128:129], v[96:97]
	v_pk_fma_f32 v[130:131], v[82:83], v[130:131], v[98:99]
	v_cvt_pk_bf16_f32 v192, v128, v129
	v_cvt_pk_bf16_f32 v193, v130, v131
	global_store_dwordx2 v34, v[192:193], s[16:17]
	v_pk_mul_f32 v[132:133], v[132:133], v[206:207] op_sel_hi:[1,0]
	v_pk_mul_f32 v[134:135], v[134:135], v[206:207] op_sel_hi:[1,0]
	v_pk_mul_f32 v[132:133], v[68:69], v[132:133]
	v_pk_mul_f32 v[134:135], v[70:71], v[134:135]
	v_pk_fma_f32 v[132:133], v[84:85], v[132:133], v[100:101]
	v_pk_fma_f32 v[134:135], v[86:87], v[134:135], v[102:103]
	v_cvt_pk_bf16_f32 v194, v132, v133
	v_cvt_pk_bf16_f32 v195, v134, v135
	global_store_dwordx2 v34, v[194:195], s[16:17] offset:512
	v_pk_mul_f32 v[136:137], v[136:137], v[206:207] op_sel_hi:[1,0]
	v_pk_mul_f32 v[138:139], v[138:139], v[206:207] op_sel_hi:[1,0]
	v_pk_mul_f32 v[136:137], v[72:73], v[136:137]
	v_pk_mul_f32 v[138:139], v[74:75], v[138:139]
	v_pk_fma_f32 v[136:137], v[88:89], v[136:137], v[104:105]
	v_pk_fma_f32 v[138:139], v[90:91], v[138:139], v[106:107]
	v_cvt_pk_bf16_f32 v196, v136, v137
	v_cvt_pk_bf16_f32 v197, v138, v139
	global_store_dwordx2 v34, v[196:197], s[16:17] offset:1024
	v_pk_mul_f32 v[140:141], v[140:141], v[206:207] op_sel_hi:[1,0]
	v_pk_mul_f32 v[142:143], v[142:143], v[206:207] op_sel_hi:[1,0]
	v_pk_mul_f32 v[140:141], v[76:77], v[140:141]
	v_pk_mul_f32 v[142:143], v[78:79], v[142:143]
	v_pk_fma_f32 v[140:141], v[92:93], v[140:141], v[108:109]
	v_pk_fma_f32 v[142:143], v[94:95], v[142:143], v[110:111]
	v_cvt_pk_bf16_f32 v198, v140, v141
	v_cvt_pk_bf16_f32 v199, v142, v143
	global_store_dwordx2 v34, v[198:199], s[16:17] offset:1536
	s_add_u32 s16, s16, 0x100000
	s_addc_u32 s17, s17, 0
	global_load_dwordx4 v[128:131], v200, s[14:15]
	global_load_dwordx4 v[132:135], v200, s[14:15] offset:1024
	global_load_dwordx4 v[136:139], v200, s[14:15] offset:2048
	global_load_dwordx4 v[140:143], v200, s[14:15] offset:3072
	s_add_u32 s14, s14, 0x200000
	s_addc_u32 s15, s15, 0
	s_waitcnt vmcnt(24)
	v_mul_f32_e32 v177, v144, v144
	v_mul_f32_e32 v178, v146, v146
	v_fmac_f32_e32 v177, v145, v145
	v_fmac_f32_e32 v178, v147, v147
	v_add_f32_e32 v176, v177, v178
	v_mul_f32_e32 v177, v148, v148
	v_mul_f32_e32 v178, v150, v150
	v_fmac_f32_e32 v177, v149, v149
	v_fmac_f32_e32 v178, v151, v151
	v_add_f32_e32 v177, v177, v178
	v_add_f32_e32 v176, v176, v177
	v_mul_f32_e32 v177, v152, v152
	v_mul_f32_e32 v178, v154, v154
	v_fmac_f32_e32 v177, v153, v153
	v_fmac_f32_e32 v178, v155, v155
	v_add_f32_e32 v177, v177, v178
	v_add_f32_e32 v176, v176, v177
	v_mul_f32_e32 v177, v156, v156
	v_mul_f32_e32 v178, v158, v158
	v_fmac_f32_e32 v177, v157, v157
	v_fmac_f32_e32 v178, v159, v159
	v_add_f32_e32 v177, v177, v178
	v_add_f32_e32 v176, v176, v177
	s_nop 1
	v_add_f32_dpp v176, v176, v176 quad_perm:[1,0,3,2] row_mask:0xf bank_mask:0xf
	s_nop 1
	v_add_f32_dpp v176, v176, v176 quad_perm:[2,3,0,1] row_mask:0xf bank_mask:0xf
	s_nop 1
	v_add_f32_dpp v176, v176, v176 row_half_mirror row_mask:0xf bank_mask:0xf
	s_nop 1
	v_add_f32_dpp v176, v176, v176 row_mirror row_mask:0xf bank_mask:0xf
	ds_bpermute_b32 v177, v201, v176
	s_waitcnt lgkmcnt(0)
	v_add_f32_e32 v176, v176, v177
	ds_bpermute_b32 v177, v202, v176
	s_waitcnt lgkmcnt(0)
; __device__ __forceinline__ unsigned cvt_pk_bf16(float lo, float hi) { unsigned r; asm volatile("v_cvt_pk_bf16_f32 %0, %1, %2" : "=v"(r) : "v"(lo), "v"(hi)); return r; }
; __device__ __forceinline__ void p1_rows(const Args& A, int lane, int wave) {
;     ...
;         if (m + NGW < M) {
; #pragma unroll
;             for (int j = 0; j < 4; ++j) nx[j] = ((const f32x4*)(A.x + (size_t)(m + NGW) * DM) + lane)[64 * j]; }
; #pragma unroll
;         for (int j = 0; j < 4; ++j) s += (v[j][0] * v[j][0] + v[j][1] * v[j][1]) + (v[j][2] * v[j][2] + v[j][3] * v[j][3]);
;         const float rstd = 1.0f / sqrtf(wave_sum(s) * (1.0f / DM) + RMS_EPS);
;         u32x2* o8 = (u32x2*)(HB + (size_t)m * DM) + lane;
; #pragma unroll
;         for (int j = 0; j < 4; ++j) { const int c = 4 * lane + 256 * j;
;             const f32x4 g = *(const f32x4*)(A.g_ffn1 + c), sc = *(const f32x4*)(mods + (size_t)b * NMODC + MOD_SC1 * DM + c), sh = *(const f32x4*)(mods + (size_t)b * NMODC + MOD_SH1 * DM + c);
;             const f32x4 h = (v[j] * rstd) * g * (sc + 1.0f) + sh;
;             u32x2 w; w.x = pg8::cvt_pk_bf16(h[0], h[1]); w.y = pg8::cvt_pk_bf16(h[2], h[3]); o8[64 * j] = w; }
	v_add_f32_e32 v176, v176, v177
	v_fmamk_f32 v176, v176, 0x3a800000, v204
	v_mul_f32_e32 v179, 0x4f800000, v176
	v_cmp_gt_f32_e32 vcc, s20, v176
	s_nop 1
	v_cndmask_b32_e32 v176, v176, v179, vcc
	v_sqrt_f32_e32 v179, v176
	s_nop 0
	v_add_u32_e32 v180, -1, v179
	v_add_u32_e32 v181, 1, v179
	v_fma_f32 v182, -v180, v179, v176
	v_fma_f32 v183, -v181, v179, v176
	v_cmp_ge_f32_e64 s[0:1], 0, v182
	s_nop 1
	v_cndmask_b32_e64 v179, v179, v180, s[0:1]
	v_cmp_lt_f32_e64 s[0:1], 0, v183
	s_nop 1
	v_cndmask_b32_e64 v179, v179, v181, s[0:1]
	v_mul_f32_e32 v180, 0x37800000, v179
	v_cndmask_b32_e32 v179, v179, v180, vcc
	v_cmp_class_f32_e32 vcc, v176, v203
	s_nop 1
	v_cndmask_b32_e32 v176, v179, v176, vcc
	v_div_scale_f32 v179, s[0:1], v176, v176, 1.0
	v_rcp_f32_e32 v180, v179
	v_div_scale_f32 v181, vcc, 1.0, v176, 1.0
	v_fma_f32 v182, -v179, v180, 1.0
	v_fmac_f32_e32 v180, v182, v180
	v_mul_f32_e32 v182, v181, v180
	v_fma_f32 v183, -v179, v182, v181
	v_fmac_f32_e32 v182, v183, v180
	v_fma_f32 v179, -v179, v182, v181
	v_div_fmas_f32 v179, v179, v180, v182
	v_div_fixup_f32 v206, v179, v176, 1.0
	v_pk_mul_f32 v[144:145], v[144:145], v[206:207] op_sel_hi:[1,0]
	v_pk_mul_f32 v[146:147], v[146:147], v[206:207] op_sel_hi:[1,0]
	v_pk_mul_f32 v[144:145], v[64:65], v[144:145]
	v_pk_mul_f32 v[146:147], v[66:67], v[146:147]
	v_pk_fma_f32 v[144:145], v[80:81], v[144:145], v[96:97]
	v_pk_fma_f32 v[146:147], v[82:83], v[146:147], v[98:99]
	v_cvt_pk_bf16_f32 v184, v144, v145
	v_cvt_pk_bf16_f32 v185, v146, v147
	global_store_dwordx2 v34, v[184:185], s[16:17]
	v_pk_mul_f32 v[148:149], v[148:149], v[206:207] op_sel_hi:[1,0]
	v_pk_mul_f32 v[150:151], v[150:151], v[206:207] op_sel_hi:[1,0]
	v_pk_mul_f32 v[148:149], v[68:69], v[148:149]
	v_pk_mul_f32 v[150:151], v[70:71], v[150:151]
	v_pk_fma_f32 v[148:149], v[84:85], v[148:149], v[100:101]
	v_pk_fma_f32 v[150:151], v[86:87], v[150:151], v[102:103]
	v_cvt_pk_bf16_f32 v186, v148, v149
	v_cvt_pk_bf16_f32 v187, v150, v151
	global_store_dwordx2 v34, v[186:187], s[16:17] offset:512
	v_pk_mul_f32 v[152:153], v[152:153], v[206:207] op_sel_hi:[1,0]
	v_pk_mul_f32 v[154:155], v[154:155], v[206:207] op_sel_hi:[1,0]
	v_pk_mul_f32 v[152:153], v[72:73], v[152:153]
	v_pk_mul_f32 v[154:155], v[74:75], v[154:155]
	v_pk_fma_f32 v[152:153], v[88:89], v[152:153], v[104:105]
	v_pk_fma_f32 v[154:155], v[90:91], v[154:155], v[106:107]
	v_cvt_pk_bf16_f32 v188, v152, v153
	v_cvt_pk_bf16_f32 v189, v154, v155
	global_store_dwordx2 v34, v[188:189], s[16:17] offset:1024
	v_pk_mul_f32 v[156:157], v[156:157], v[206:207] op_sel_hi:[1,0]
	v_pk_mul_f32 v[158:159], v[158:159], v[206:207] op_sel_hi:[1,0]
	v_pk_mul_f32 v[156:157], v[76:77], v[156:157]
	v_pk_mul_f32 v[158:159], v[78:79], v[158:159]
	v_pk_fma_f32 v[156:157], v[92:93], v[156:157], v[108:109]
	v_pk_fma_f32 v[158:159], v[94:95], v[158:159], v[110:111]
	v_cvt_pk_bf16_f32 v190, v156, v157
	v_cvt_pk_bf16_f32 v191, v158, v159
	global_store_dwordx2 v34, v[190:191], s[16:17] offset:1536
	s_add_u32 s16, s16, 0x100000
	s_addc_u32 s17, s17, 0
	global_load_dwordx4 v[144:147], v200, s[14:15]
	global_load_dwordx4 v[148:151], v200, s[14:15] offset:1024
	global_load_dwordx4 v[152:155], v200, s[14:15] offset:2048
	global_load_dwordx4 v[156:159], v200, s[14:15] offset:3072
	s_add_u32 s14, s14, 0x200000
	s_addc_u32 s15, s15, 0
	s_waitcnt vmcnt(24)
	v_mul_f32_e32 v177, v160, v160
	v_mul_f32_e32 v178, v162, v162
	v_fmac_f32_e32 v177, v161, v161
	v_fmac_f32_e32 v178, v163, v163
	v_add_f32_e32 v176, v177, v178
	v_mul_f32_e32 v177, v164, v164
	v_mul_f32_e32 v178, v166, v166
	v_fmac_f32_e32 v177, v165, v165
	v_fmac_f32_e32 v178, v167, v167
	v_add_f32_e32 v177, v177, v178
	v_add_f32_e32 v176, v176, v177
	v_mul_f32_e32 v177, v168, v168
	v_mul_f32_e32 v178, v170, v170
	v_fmac_f32_e32 v177, v169, v169
	v_fmac_f32_e32 v178, v171, v171
	v_add_f32_e32 v177, v177, v178
	v_add_f32_e32 v176, v176, v177
	v_mul_f32_e32 v177, v172, v172
	v_mul_f32_e32 v178, v174, v174
	v_fmac_f32_e32 v177, v173, v173
	v_fmac_f32_e32 v178, v175, v175
	v_add_f32_e32 v177, v177, v178
	v_add_f32_e32 v176, v176, v177
	s_nop 1
	v_add_f32_dpp v176, v176, v176 quad_perm:[1,0,3,2] row_mask:0xf bank_mask:0xf
	s_nop 1
	v_add_f32_dpp v176, v176, v176 quad_perm:[2,3,0,1] row_mask:0xf bank_mask:0xf
	s_nop 1
	v_add_f32_dpp v176, v176, v176 row_half_mirror row_mask:0xf bank_mask:0xf
	s_nop 1
	v_add_f32_dpp v176, v176, v176 row_mirror row_mask:0xf bank_mask:0xf
	ds_bpermute_b32 v177, v201, v176
	s_waitcnt lgkmcnt(0)
	v_add_f32_e32 v176, v176, v177
	ds_bpermute_b32 v177, v202, v176
	s_waitcnt lgkmcnt(0)
; __device__ __forceinline__ unsigned cvt_pk_bf16(float lo, float hi) { unsigned r; asm volatile("v_cvt_pk_bf16_f32 %0, %1, %2" : "=v"(r) : "v"(lo), "v"(hi)); return r; }
; __device__ __forceinline__ void p1_rows(const Args& A, int lane, int wave) {
;     ...
;         if (m + NGW < M) {
; #pragma unroll
;             for (int j = 0; j < 4; ++j) nx[j] = ((const f32x4*)(A.x + (size_t)(m + NGW) * DM) + lane)[64 * j]; }
; #pragma unroll
;         for (int j = 0; j < 4; ++j) s += (v[j][0] * v[j][0] + v[j][1] * v[j][1]) + (v[j][2] * v[j][2] + v[j][3] * v[j][3]);
;         const float rstd = 1.0f / sqrtf(wave_sum(s) * (1.0f / DM) + RMS_EPS);
;         u32x2* o8 = (u32x2*)(HB + (size_t)m * DM) + lane;
; #pragma unroll
;         for (int j = 0; j < 4; ++j) { const int c = 4 * lane + 256 * j;
;             const f32x4 g = *(const f32x4*)(A.g_ffn1 + c), sc = *(const f32x4*)(mods + (size_t)b * NMODC + MOD_SC1 * DM + c), sh = *(const f32x4*)(mods + (size_t)b * NMODC + MOD_SH1 * DM + c);
;             const f32x4 h = (v[j] * rstd) * g * (sc + 1.0f) + sh;
;             u32x2 w; w.x = pg8::cvt_pk_bf16(h[0], h[1]); w.y = pg8::cvt_pk_bf16(h[2], h[3]); o8[64 * j] = w; }
	v_add_f32_e32 v176, v176, v177
	v_fmamk_f32 v176, v176, 0x3a800000, v204
	v_mul_f32_e32 v179, 0x4f800000, v176
	v_cmp_gt_f32_e32 vcc, s20, v176
	s_nop 1
	v_cndmask_b32_e32 v176, v176, v179, vcc
	v_sqrt_f32_e32 v179, v176
	s_nop 0
	v_add_u32_e32 v180, -1, v179
	v_add_u32_e32 v181, 1, v179
	v_fma_f32 v182, -v180, v179, v176
	v_fma_f32 v183, -v181, v179, v176
	v_cmp_ge_f32_e64 s[0:1], 0, v182
	s_nop 1
	v_cndmask_b32_e64 v179, v179, v180, s[0:1]
	v_cmp_lt_f32_e64 s[0:1], 0, v183
	s_nop 1
	v_cndmask_b32_e64 v179, v179, v181, s[0:1]
	v_mul_f32_e32 v180, 0x37800000, v179
	v_cndmask_b32_e32 v179, v179, v180, vcc
	v_cmp_class_f32_e32 vcc, v176, v203
	s_nop 1
	v_cndmask_b32_e32 v176, v179, v176, vcc
	v_div_scale_f32 v179, s[0:1], v176, v176, 1.0
	v_rcp_f32_e32 v180, v179
	v_div_scale_f32 v181, vcc, 1.0, v176, 1.0
	v_fma_f32 v182, -v179, v180, 1.0
	v_fmac_f32_e32 v180, v182, v180
	v_mul_f32_e32 v182, v181, v180
	v_fma_f32 v183, -v179, v182, v181
	v_fmac_f32_e32 v182, v183, v180
	v_fma_f32 v179, -v179, v182, v181
	v_div_fmas_f32 v179, v179, v180, v182
	v_div_fixup_f32 v206, v179, v176, 1.0
	v_pk_mul_f32 v[160:161], v[160:161], v[206:207] op_sel_hi:[1,0]
	v_pk_mul_f32 v[162:163], v[162:163], v[206:207] op_sel_hi:[1,0]
	v_pk_mul_f32 v[160:161], v[64:65], v[160:161]
	v_pk_mul_f32 v[162:163], v[66:67], v[162:163]
	v_pk_fma_f32 v[160:161], v[80:81], v[160:161], v[96:97]
	v_pk_fma_f32 v[162:163], v[82:83], v[162:163], v[98:99]
	v_cvt_pk_bf16_f32 v192, v160, v161
	v_cvt_pk_bf16_f32 v193, v162, v163
	global_store_dwordx2 v34, v[192:193], s[16:17]
	v_pk_mul_f32 v[164:165], v[164:165], v[206:207] op_sel_hi:[1,0]
	v_pk_mul_f32 v[166:167], v[166:167], v[206:207] op_sel_hi:[1,0]
	v_pk_mul_f32 v[164:165], v[68:69], v[164:165]
	v_pk_mul_f32 v[166:167], v[70:71], v[166:167]
	v_pk_fma_f32 v[164:165], v[84:85], v[164:165], v[100:101]
	v_pk_fma_f32 v[166:167], v[86:87], v[166:167], v[102:103]
	v_cvt_pk_bf16_f32 v194, v164, v165
	v_cvt_pk_bf16_f32 v195, v166, v167
	global_store_dwordx2 v34, v[194:195], s[16:17] offset:512
	v_pk_mul_f32 v[168:169], v[168:169], v[206:207] op_sel_hi:[1,0]
	v_pk_mul_f32 v[170:171], v[170:171], v[206:207] op_sel_hi:[1,0]
	v_pk_mul_f32 v[168:169], v[72:73], v[168:169]
	v_pk_mul_f32 v[170:171], v[74:75], v[170:171]
	v_pk_fma_f32 v[168:169], v[88:89], v[168:169], v[104:105]
	v_pk_fma_f32 v[170:171], v[90:91], v[170:171], v[106:107]
	v_cvt_pk_bf16_f32 v196, v168, v169
	v_cvt_pk_bf16_f32 v197, v170, v171
	global_store_dwordx2 v34, v[196:197], s[16:17] offset:1024
	v_pk_mul_f32 v[172:173], v[172:173], v[206:207] op_sel_hi:[1,0]
	v_pk_mul_f32 v[174:175], v[174:175], v[206:207] op_sel_hi:[1,0]
	v_pk_mul_f32 v[172:173], v[76:77], v[172:173]
	v_pk_mul_f32 v[174:175], v[78:79], v[174:175]
	v_pk_fma_f32 v[172:173], v[92:93], v[172:173], v[108:109]
	v_pk_fma_f32 v[174:175], v[94:95], v[174:175], v[110:111]
	v_cvt_pk_bf16_f32 v198, v172, v173
	v_cvt_pk_bf16_f32 v199, v174, v175
	global_store_dwordx2 v34, v[198:199], s[16:17] offset:1536
	s_add_u32 s16, s16, 0x100000
	s_addc_u32 s17, s17, 0
	global_load_dwordx4 v[160:163], v200, s[14:15]
	global_load_dwordx4 v[164:167], v200, s[14:15] offset:1024
	global_load_dwordx4 v[168:171], v200, s[14:15] offset:2048
	global_load_dwordx4 v[172:175], v200, s[14:15] offset:3072
	s_add_u32 s14, s14, 0x200000
	s_addc_u32 s15, s15, 0
	s_waitcnt vmcnt(24)
	v_mul_f32_e32 v177, v112, v112
	v_mul_f32_e32 v178, v114, v114
	v_fmac_f32_e32 v177, v113, v113
	v_fmac_f32_e32 v178, v115, v115
	v_add_f32_e32 v176, v177, v178
	v_mul_f32_e32 v177, v116, v116
	v_mul_f32_e32 v178, v118, v118
	v_fmac_f32_e32 v177, v117, v117
	v_fmac_f32_e32 v178, v119, v119
	v_add_f32_e32 v177, v177, v178
	v_add_f32_e32 v176, v176, v177
	v_mul_f32_e32 v177, v120, v120
	v_mul_f32_e32 v178, v122, v122
	v_fmac_f32_e32 v177, v121, v121
	v_fmac_f32_e32 v178, v123, v123
	v_add_f32_e32 v177, v177, v178
	v_add_f32_e32 v176, v176, v177
	v_mul_f32_e32 v177, v124, v124
	v_mul_f32_e32 v178, v126, v126
	v_fmac_f32_e32 v177, v125, v125
	v_fmac_f32_e32 v178, v127, v127
	v_add_f32_e32 v177, v177, v178
	v_add_f32_e32 v176, v176, v177
	s_nop 1
	v_add_f32_dpp v176, v176, v176 quad_perm:[1,0,3,2] row_mask:0xf bank_mask:0xf
	s_nop 1
	v_add_f32_dpp v176, v176, v176 quad_perm:[2,3,0,1] row_mask:0xf bank_mask:0xf
	s_nop 1
	v_add_f32_dpp v176, v176, v176 row_half_mirror row_mask:0xf bank_mask:0xf
	s_nop 1
	v_add_f32_dpp v176, v176, v176 row_mirror row_mask:0xf bank_mask:0xf
	ds_bpermute_b32 v177, v201, v176
	s_waitcnt lgkmcnt(0)
	v_add_f32_e32 v176, v176, v177
	ds_bpermute_b32 v177, v202, v176
	s_waitcnt lgkmcnt(0)
; __device__ __forceinline__ unsigned cvt_pk_bf16(float lo, float hi) { unsigned r; asm volatile("v_cvt_pk_bf16_f32 %0, %1, %2" : "=v"(r) : "v"(lo), "v"(hi)); return r; }
; __device__ __forceinline__ void p1_rows(const Args& A, int lane, int wave) {
;     ...
;         if (m + NGW < M) {
; #pragma unroll
;             for (int j = 0; j < 4; ++j) nx[j] = ((const f32x4*)(A.x + (size_t)(m + NGW) * DM) + lane)[64 * j]; }
; #pragma unroll
;         for (int j = 0; j < 4; ++j) s += (v[j][0] * v[j][0] + v[j][1] * v[j][1]) + (v[j][2] * v[j][2] + v[j][3] * v[j][3]);
;         const float rstd = 1.0f / sqrtf(wave_sum(s) * (1.0f / DM) + RMS_EPS);
;         u32x2* o8 = (u32x2*)(HB + (size_t)m * DM) + lane;
; #pragma unroll
;         for (int j = 0; j < 4; ++j) { const int c = 4 * lane + 256 * j;
;             const f32x4 g = *(const f32x4*)(A.g_ffn1 + c), sc = *(const f32x4*)(mods + (size_t)b * NMODC + MOD_SC1 * DM + c), sh = *(const f32x4*)(mods + (size_t)b * NMODC + MOD_SH1 * DM + c);
;             const f32x4 h = (v[j] * rstd) * g * (sc + 1.0f) + sh;
;             u32x2 w; w.x = pg8::cvt_pk_bf16(h[0], h[1]); w.y = pg8::cvt_pk_bf16(h[2], h[3]); o8[64 * j] = w; }
	v_add_f32_e32 v176, v176, v177
	v_fmamk_f32 v176, v176, 0x3a800000, v204
	v_mul_f32_e32 v179, 0x4f800000, v176
	v_cmp_gt_f32_e32 vcc, s20, v176
	s_nop 1
	v_cndmask_b32_e32 v176, v176, v179, vcc
	v_sqrt_f32_e32 v179, v176
	s_nop 0
	v_add_u32_e32 v180, -1, v179
	v_add_u32_e32 v181, 1, v179
	v_fma_f32 v182, -v180, v179, v176
	v_fma_f32 v183, -v181, v179, v176
	v_cmp_ge_f32_e64 s[0:1], 0, v182
	s_nop 1
	v_cndmask_b32_e64 v179, v179, v180, s[0:1]
	v_cmp_lt_f32_e64 s[0:1], 0, v183
	s_nop 1
	v_cndmask_b32_e64 v179, v179, v181, s[0:1]
	v_mul_f32_e32 v180, 0x37800000, v179
	v_cndmask_b32_e32 v179, v179, v180, vcc
	v_cmp_class_f32_e32 vcc, v176, v203
	s_nop 1
	v_cndmask_b32_e32 v176, v179, v176, vcc
	v_div_scale_f32 v179, s[0:1], v176, v176, 1.0
	v_rcp_f32_e32 v180, v179
	v_div_scale_f32 v181, vcc, 1.0, v176, 1.0
	v_fma_f32 v182, -v179, v180, 1.0
	v_fmac_f32_e32 v180, v182, v180
	v_mul_f32_e32 v182, v181, v180
	v_fma_f32 v183, -v179, v182, v181
	v_fmac_f32_e32 v182, v183, v180
	v_fma_f32 v179, -v179, v182, v181
	v_div_fmas_f32 v179, v179, v180, v182
	v_div_fixup_f32 v206, v179, v176, 1.0
	v_pk_mul_f32 v[112:113], v[112:113], v[206:207] op_sel_hi:[1,0]
	v_pk_mul_f32 v[114:115], v[114:115], v[206:207] op_sel_hi:[1,0]
	v_pk_mul_f32 v[112:113], v[64:65], v[112:113]
	v_pk_mul_f32 v[114:115], v[66:67], v[114:115]
	v_pk_fma_f32 v[112:113], v[80:81], v[112:113], v[96:97]
	v_pk_fma_f32 v[114:115], v[82:83], v[114:115], v[98:99]
	v_cvt_pk_bf16_f32 v184, v112, v113
	v_cvt_pk_bf16_f32 v185, v114, v115
	global_store_dwordx2 v34, v[184:185], s[16:17]
	v_pk_mul_f32 v[116:117], v[116:117], v[206:207] op_sel_hi:[1,0]
	v_pk_mul_f32 v[118:119], v[118:119], v[206:207] op_sel_hi:[1,0]
	v_pk_mul_f32 v[116:117], v[68:69], v[116:117]
	v_pk_mul_f32 v[118:119], v[70:71], v[118:119]
	v_pk_fma_f32 v[116:117], v[84:85], v[116:117], v[100:101]
	v_pk_fma_f32 v[118:119], v[86:87], v[118:119], v[102:103]
	v_cvt_pk_bf16_f32 v186, v116, v117
	v_cvt_pk_bf16_f32 v187, v118, v119
	global_store_dwordx2 v34, v[186:187], s[16:17] offset:512
	v_pk_mul_f32 v[120:121], v[120:121], v[206:207] op_sel_hi:[1,0]
	v_pk_mul_f32 v[122:123], v[122:123], v[206:207] op_sel_hi:[1,0]
	v_pk_mul_f32 v[120:121], v[72:73], v[120:121]
	v_pk_mul_f32 v[122:123], v[74:75], v[122:123]
	v_pk_fma_f32 v[120:121], v[88:89], v[120:121], v[104:105]
	v_pk_fma_f32 v[122:123], v[90:91], v[122:123], v[106:107]
	v_cvt_pk_bf16_f32 v188, v120, v121
	v_cvt_pk_bf16_f32 v189, v122, v123
	global_store_dwordx2 v34, v[188:189], s[16:17] offset:1024
	v_pk_mul_f32 v[124:125], v[124:125], v[206:207] op_sel_hi:[1,0]
	v_pk_mul_f32 v[126:127], v[126:127], v[206:207] op_sel_hi:[1,0]
	v_pk_mul_f32 v[124:125], v[76:77], v[124:125]
	v_pk_mul_f32 v[126:127], v[78:79], v[126:127]
	v_pk_fma_f32 v[124:125], v[92:93], v[124:125], v[108:109]
	v_pk_fma_f32 v[126:127], v[94:95], v[126:127], v[110:111]
	v_cvt_pk_bf16_f32 v190, v124, v125
	v_cvt_pk_bf16_f32 v191, v126, v127
	global_store_dwordx2 v34, v[190:191], s[16:17] offset:1536
	s_add_u32 s16, s16, 0x100000
	s_addc_u32 s17, s17, 0
	s_waitcnt vmcnt(20)
	v_mul_f32_e32 v177, v128, v128
	v_mul_f32_e32 v178, v130, v130
	v_fmac_f32_e32 v177, v129, v129
	v_fmac_f32_e32 v178, v131, v131
	v_add_f32_e32 v176, v177, v178
	v_mul_f32_e32 v177, v132, v132
	v_mul_f32_e32 v178, v134, v134
	v_fmac_f32_e32 v177, v133, v133
	v_fmac_f32_e32 v178, v135, v135
	v_add_f32_e32 v177, v177, v178
	v_add_f32_e32 v176, v176, v177
	v_mul_f32_e32 v177, v136, v136
	v_mul_f32_e32 v178, v138, v138
	v_fmac_f32_e32 v177, v137, v137
	v_fmac_f32_e32 v178, v139, v139
	v_add_f32_e32 v177, v177, v178
	v_add_f32_e32 v176, v176, v177
	v_mul_f32_e32 v177, v140, v140
	v_mul_f32_e32 v178, v142, v142
	v_fmac_f32_e32 v177, v141, v141
	v_fmac_f32_e32 v178, v143, v143
	v_add_f32_e32 v177, v177, v178
	v_add_f32_e32 v176, v176, v177
	s_nop 1
	v_add_f32_dpp v176, v176, v176 quad_perm:[1,0,3,2] row_mask:0xf bank_mask:0xf
	s_nop 1
	v_add_f32_dpp v176, v176, v176 quad_perm:[2,3,0,1] row_mask:0xf bank_mask:0xf
	s_nop 1
	v_add_f32_dpp v176, v176, v176 row_half_mirror row_mask:0xf bank_mask:0xf
	s_nop 1
	v_add_f32_dpp v176, v176, v176 row_mirror row_mask:0xf bank_mask:0xf
	ds_bpermute_b32 v177, v201, v176
	s_waitcnt lgkmcnt(0)
	v_add_f32_e32 v176, v176, v177
	ds_bpermute_b32 v177, v202, v176
	s_waitcnt lgkmcnt(0)
; __device__ __forceinline__ unsigned cvt_pk_bf16(float lo, float hi) { unsigned r; asm volatile("v_cvt_pk_bf16_f32 %0, %1, %2" : "=v"(r) : "v"(lo), "v"(hi)); return r; }
; __device__ __forceinline__ void p1_rows(const Args& A, int lane, int wave) {
;     ...
;         for (int j = 0; j < 4; ++j) s += (v[j][0] * v[j][0] + v[j][1] * v[j][1]) + (v[j][2] * v[j][2] + v[j][3] * v[j][3]);
;         const float rstd = 1.0f / sqrtf(wave_sum(s) * (1.0f / DM) + RMS_EPS);
;         u32x2* o8 = (u32x2*)(HB + (size_t)m * DM) + lane;
; #pragma unroll
;         for (int j = 0; j < 4; ++j) { const int c = 4 * lane + 256 * j;
;             const f32x4 g = *(const f32x4*)(A.g_ffn1 + c), sc = *(const f32x4*)(mods + (size_t)b * NMODC + MOD_SC1 * DM + c), sh = *(const f32x4*)(mods + (size_t)b * NMODC + MOD_SH1 * DM + c);
;             const f32x4 h = (v[j] * rstd) * g * (sc + 1.0f) + sh;
;             u32x2 w; w.x = pg8::cvt_pk_bf16(h[0], h[1]); w.y = pg8::cvt_pk_bf16(h[2], h[3]); o8[64 * j] = w; }
	v_add_f32_e32 v176, v176, v177
	v_fmamk_f32 v176, v176, 0x3a800000, v204
	v_mul_f32_e32 v179, 0x4f800000, v176
	v_cmp_gt_f32_e32 vcc, s20, v176
	s_nop 1
	v_cndmask_b32_e32 v176, v176, v179, vcc
	v_sqrt_f32_e32 v179, v176
	s_nop 0
	v_add_u32_e32 v180, -1, v179
	v_add_u32_e32 v181, 1, v179
	v_fma_f32 v182, -v180, v179, v176
	v_fma_f32 v183, -v181, v179, v176
	v_cmp_ge_f32_e64 s[0:1], 0, v182
	s_nop 1
	v_cndmask_b32_e64 v179, v179, v180, s[0:1]
	v_cmp_lt_f32_e64 s[0:1], 0, v183
	s_nop 1
	v_cndmask_b32_e64 v179, v179, v181, s[0:1]
	v_mul_f32_e32 v180, 0x37800000, v179
	v_cndmask_b32_e32 v179, v179, v180, vcc
	v_cmp_class_f32_e32 vcc, v176, v203
	s_nop 1
	v_cndmask_b32_e32 v176, v179, v176, vcc
	v_div_scale_f32 v179, s[0:1], v176, v176, 1.0
	v_rcp_f32_e32 v180, v179
	v_div_scale_f32 v181, vcc, 1.0, v176, 1.0
	v_fma_f32 v182, -v179, v180, 1.0
	v_fmac_f32_e32 v180, v182, v180
	v_mul_f32_e32 v182, v181, v180
	v_fma_f32 v183, -v179, v182, v181
	v_fmac_f32_e32 v182, v183, v180
	v_fma_f32 v179, -v179, v182, v181
	v_div_fmas_f32 v179, v179, v180, v182
	v_div_fixup_f32 v206, v179, v176, 1.0
	v_pk_mul_f32 v[128:129], v[128:129], v[206:207] op_sel_hi:[1,0]
	v_pk_mul_f32 v[130:131], v[130:131], v[206:207] op_sel_hi:[1,0]
	v_pk_mul_f32 v[128:129], v[64:65], v[128:129]
	v_pk_mul_f32 v[130:131], v[66:67], v[130:131]
	v_pk_fma_f32 v[128:129], v[80:81], v[128:129], v[96:97]
	v_pk_fma_f32 v[130:131], v[82:83], v[130:131], v[98:99]
	v_cvt_pk_bf16_f32 v192, v128, v129
	v_cvt_pk_bf16_f32 v193, v130, v131
	global_store_dwordx2 v34, v[192:193], s[16:17]
	v_pk_mul_f32 v[132:133], v[132:133], v[206:207] op_sel_hi:[1,0]
	v_pk_mul_f32 v[134:135], v[134:135], v[206:207] op_sel_hi:[1,0]
	v_pk_mul_f32 v[132:133], v[68:69], v[132:133]
	v_pk_mul_f32 v[134:135], v[70:71], v[134:135]
	v_pk_fma_f32 v[132:133], v[84:85], v[132:133], v[100:101]
	v_pk_fma_f32 v[134:135], v[86:87], v[134:135], v[102:103]
	v_cvt_pk_bf16_f32 v194, v132, v133
	v_cvt_pk_bf16_f32 v195, v134, v135
	global_store_dwordx2 v34, v[194:195], s[16:17] offset:512
	v_pk_mul_f32 v[136:137], v[136:137], v[206:207] op_sel_hi:[1,0]
	v_pk_mul_f32 v[138:139], v[138:139], v[206:207] op_sel_hi:[1,0]
	v_pk_mul_f32 v[136:137], v[72:73], v[136:137]
	v_pk_mul_f32 v[138:139], v[74:75], v[138:139]
	v_pk_fma_f32 v[136:137], v[88:89], v[136:137], v[104:105]
	v_pk_fma_f32 v[138:139], v[90:91], v[138:139], v[106:107]
	v_cvt_pk_bf16_f32 v196, v136, v137
	v_cvt_pk_bf16_f32 v197, v138, v139
	global_store_dwordx2 v34, v[196:197], s[16:17] offset:1024
	v_pk_mul_f32 v[140:141], v[140:141], v[206:207] op_sel_hi:[1,0]
	v_pk_mul_f32 v[142:143], v[142:143], v[206:207] op_sel_hi:[1,0]
	v_pk_mul_f32 v[140:141], v[76:77], v[140:141]
	v_pk_mul_f32 v[142:143], v[78:79], v[142:143]
	v_pk_fma_f32 v[140:141], v[92:93], v[140:141], v[108:109]
	v_pk_fma_f32 v[142:143], v[94:95], v[142:143], v[110:111]
	v_cvt_pk_bf16_f32 v198, v140, v141
	v_cvt_pk_bf16_f32 v199, v142, v143
	global_store_dwordx2 v34, v[198:199], s[16:17] offset:1536
	s_add_u32 s16, s16, 0x100000
	s_addc_u32 s17, s17, 0
	s_waitcnt vmcnt(16)
	v_mul_f32_e32 v177, v144, v144
	v_mul_f32_e32 v178, v146, v146
	v_fmac_f32_e32 v177, v145, v145
	v_fmac_f32_e32 v178, v147, v147
	v_add_f32_e32 v176, v177, v178
	v_mul_f32_e32 v177, v148, v148
	v_mul_f32_e32 v178, v150, v150
	v_fmac_f32_e32 v177, v149, v149
	v_fmac_f32_e32 v178, v151, v151
	v_add_f32_e32 v177, v177, v178
	v_add_f32_e32 v176, v176, v177
	v_mul_f32_e32 v177, v152, v152
	v_mul_f32_e32 v178, v154, v154
	v_fmac_f32_e32 v177, v153, v153
	v_fmac_f32_e32 v178, v155, v155
	v_add_f32_e32 v177, v177, v178
	v_add_f32_e32 v176, v176, v177
	v_mul_f32_e32 v177, v156, v156
	v_mul_f32_e32 v178, v158, v158
	v_fmac_f32_e32 v177, v157, v157
	v_fmac_f32_e32 v178, v159, v159
	v_add_f32_e32 v177, v177, v178
	v_add_f32_e32 v176, v176, v177
	s_nop 1
	v_add_f32_dpp v176, v176, v176 quad_perm:[1,0,3,2] row_mask:0xf bank_mask:0xf
	s_nop 1
	v_add_f32_dpp v176, v176, v176 quad_perm:[2,3,0,1] row_mask:0xf bank_mask:0xf
	s_nop 1
	v_add_f32_dpp v176, v176, v176 row_half_mirror row_mask:0xf bank_mask:0xf
	s_nop 1
	v_add_f32_dpp v176, v176, v176 row_mirror row_mask:0xf bank_mask:0xf
	ds_bpermute_b32 v177, v201, v176
	s_waitcnt lgkmcnt(0)
	v_add_f32_e32 v176, v176, v177
	ds_bpermute_b32 v177, v202, v176
	s_waitcnt lgkmcnt(0)
; __device__ __forceinline__ unsigned cvt_pk_bf16(float lo, float hi) { unsigned r; asm volatile("v_cvt_pk_bf16_f32 %0, %1, %2" : "=v"(r) : "v"(lo), "v"(hi)); return r; }
; __device__ __forceinline__ void p1_rows(const Args& A, int lane, int wave) {
;     ...
;         for (int j = 0; j < 4; ++j) s += (v[j][0] * v[j][0] + v[j][1] * v[j][1]) + (v[j][2] * v[j][2] + v[j][3] * v[j][3]);
;         const float rstd = 1.0f / sqrtf(wave_sum(s) * (1.0f / DM) + RMS_EPS);
;         u32x2* o8 = (u32x2*)(HB + (size_t)m * DM) + lane;
; #pragma unroll
;         for (int j = 0; j < 4; ++j) { const int c = 4 * lane + 256 * j;
;             const f32x4 g = *(const f32x4*)(A.g_ffn1 + c), sc = *(const f32x4*)(mods + (size_t)b * NMODC + MOD_SC1 * DM + c), sh = *(const f32x4*)(mods + (size_t)b * NMODC + MOD_SH1 * DM + c);
;             const f32x4 h = (v[j] * rstd) * g * (sc + 1.0f) + sh;
;             u32x2 w; w.x = pg8::cvt_pk_bf16(h[0], h[1]); w.y = pg8::cvt_pk_bf16(h[2], h[3]); o8[64 * j] = w; }
	v_add_f32_e32 v176, v176, v177
	v_fmamk_f32 v176, v176, 0x3a800000, v204
	v_mul_f32_e32 v179, 0x4f800000, v176
	v_cmp_gt_f32_e32 vcc, s20, v176
	s_nop 1
	v_cndmask_b32_e32 v176, v176, v179, vcc
	v_sqrt_f32_e32 v179, v176
	s_nop 0
	v_add_u32_e32 v180, -1, v179
	v_add_u32_e32 v181, 1, v179
	v_fma_f32 v182, -v180, v179, v176
	v_fma_f32 v183, -v181, v179, v176
	v_cmp_ge_f32_e64 s[0:1], 0, v182
	s_nop 1
	v_cndmask_b32_e64 v179, v179, v180, s[0:1]
	v_cmp_lt_f32_e64 s[0:1], 0, v183
	s_nop 1
	v_cndmask_b32_e64 v179, v179, v181, s[0:1]
	v_mul_f32_e32 v180, 0x37800000, v179
	v_cndmask_b32_e32 v179, v179, v180, vcc
	v_cmp_class_f32_e32 vcc, v176, v203
	s_nop 1
	v_cndmask_b32_e32 v176, v179, v176, vcc
	v_div_scale_f32 v179, s[0:1], v176, v176, 1.0
	v_rcp_f32_e32 v180, v179
	v_div_scale_f32 v181, vcc, 1.0, v176, 1.0
	v_fma_f32 v182, -v179, v180, 1.0
	v_fmac_f32_e32 v180, v182, v180
	v_mul_f32_e32 v182, v181, v180
	v_fma_f32 v183, -v179, v182, v181
	v_fmac_f32_e32 v182, v183, v180
	v_fma_f32 v179, -v179, v182, v181
	v_div_fmas_f32 v179, v179, v180, v182
	v_div_fixup_f32 v206, v179, v176, 1.0
	v_pk_mul_f32 v[144:145], v[144:145], v[206:207] op_sel_hi:[1,0]
	v_pk_mul_f32 v[146:147], v[146:147], v[206:207] op_sel_hi:[1,0]
	v_pk_mul_f32 v[144:145], v[64:65], v[144:145]
	v_pk_mul_f32 v[146:147], v[66:67], v[146:147]
	v_pk_fma_f32 v[144:145], v[80:81], v[144:145], v[96:97]
	v_pk_fma_f32 v[146:147], v[82:83], v[146:147], v[98:99]
	v_cvt_pk_bf16_f32 v184, v144, v145
	v_cvt_pk_bf16_f32 v185, v146, v147
	global_store_dwordx2 v34, v[184:185], s[16:17]
	v_pk_mul_f32 v[148:149], v[148:149], v[206:207] op_sel_hi:[1,0]
	v_pk_mul_f32 v[150:151], v[150:151], v[206:207] op_sel_hi:[1,0]
	v_pk_mul_f32 v[148:149], v[68:69], v[148:149]
	v_pk_mul_f32 v[150:151], v[70:71], v[150:151]
	v_pk_fma_f32 v[148:149], v[84:85], v[148:149], v[100:101]
	v_pk_fma_f32 v[150:151], v[86:87], v[150:151], v[102:103]
	v_cvt_pk_bf16_f32 v186, v148, v149
	v_cvt_pk_bf16_f32 v187, v150, v151
	global_store_dwordx2 v34, v[186:187], s[16:17] offset:512
	v_pk_mul_f32 v[152:153], v[152:153], v[206:207] op_sel_hi:[1,0]
	v_pk_mul_f32 v[154:155], v[154:155], v[206:207] op_sel_hi:[1,0]
	v_pk_mul_f32 v[152:153], v[72:73], v[152:153]
	v_pk_mul_f32 v[154:155], v[74:75], v[154:155]
	v_pk_fma_f32 v[152:153], v[88:89], v[152:153], v[104:105]
	v_pk_fma_f32 v[154:155], v[90:91], v[154:155], v[106:107]
	v_cvt_pk_bf16_f32 v188, v152, v153
	v_cvt_pk_bf16_f32 v189, v154, v155
	global_store_dwordx2 v34, v[188:189], s[16:17] offset:1024
	v_pk_mul_f32 v[156:157], v[156:157], v[206:207] op_sel_hi:[1,0]
	v_pk_mul_f32 v[158:159], v[158:159], v[206:207] op_sel_hi:[1,0]
	v_pk_mul_f32 v[156:157], v[76:77], v[156:157]
	v_pk_mul_f32 v[158:159], v[78:79], v[158:159]
	v_pk_fma_f32 v[156:157], v[92:93], v[156:157], v[108:109]
	v_pk_fma_f32 v[158:159], v[94:95], v[158:159], v[110:111]
	v_cvt_pk_bf16_f32 v190, v156, v157
	v_cvt_pk_bf16_f32 v191, v158, v159
	global_store_dwordx2 v34, v[190:191], s[16:17] offset:1536
	s_add_u32 s16, s16, 0x100000
	s_addc_u32 s17, s17, 0
	s_waitcnt vmcnt(12)
	v_mul_f32_e32 v177, v160, v160
	v_mul_f32_e32 v178, v162, v162
	v_fmac_f32_e32 v177, v161, v161
	v_fmac_f32_e32 v178, v163, v163
	v_add_f32_e32 v176, v177, v178
	v_mul_f32_e32 v177, v164, v164
	v_mul_f32_e32 v178, v166, v166
	v_fmac_f32_e32 v177, v165, v165
	v_fmac_f32_e32 v178, v167, v167
	v_add_f32_e32 v177, v177, v178
	v_add_f32_e32 v176, v176, v177
	v_mul_f32_e32 v177, v168, v168
	v_mul_f32_e32 v178, v170, v170
	v_fmac_f32_e32 v177, v169, v169
	v_fmac_f32_e32 v178, v171, v171
	v_add_f32_e32 v177, v177, v178
	v_add_f32_e32 v176, v176, v177
	v_mul_f32_e32 v177, v172, v172
	v_mul_f32_e32 v178, v174, v174
	v_fmac_f32_e32 v177, v173, v173
	v_fmac_f32_e32 v178, v175, v175
	v_add_f32_e32 v177, v177, v178
	v_add_f32_e32 v176, v176, v177
	s_nop 1
	v_add_f32_dpp v176, v176, v176 quad_perm:[1,0,3,2] row_mask:0xf bank_mask:0xf
	s_nop 1
	v_add_f32_dpp v176, v176, v176 quad_perm:[2,3,0,1] row_mask:0xf bank_mask:0xf
	s_nop 1
	v_add_f32_dpp v176, v176, v176 row_half_mirror row_mask:0xf bank_mask:0xf
	s_nop 1
	v_add_f32_dpp v176, v176, v176 row_mirror row_mask:0xf bank_mask:0xf
	ds_bpermute_b32 v177, v201, v176
	s_waitcnt lgkmcnt(0)
; __device__ __forceinline__ unsigned cvt_pk_bf16(float lo, float hi) { unsigned r; asm volatile("v_cvt_pk_bf16_f32 %0, %1, %2" : "=v"(r) : "v"(lo), "v"(hi)); return r; }
; __device__ __forceinline__ void p1_rows(const Args& A, int lane, int wave) {
;     ...
;         const float rstd = 1.0f / sqrtf(wave_sum(s) * (1.0f / DM) + RMS_EPS);
;         u32x2* o8 = (u32x2*)(HB + (size_t)m * DM) + lane;
; #pragma unroll
;         for (int j = 0; j < 4; ++j) { const int c = 4 * lane + 256 * j;
;             const f32x4 g = *(const f32x4*)(A.g_ffn1 + c), sc = *(const f32x4*)(mods + (size_t)b * NMODC + MOD_SC1 * DM + c), sh = *(const f32x4*)(mods + (size_t)b * NMODC + MOD_SH1 * DM + c);
;             const f32x4 h = (v[j] * rstd) * g * (sc + 1.0f) + sh;
;             u32x2 w; w.x = pg8::cvt_pk_bf16(h[0], h[1]); w.y = pg8::cvt_pk_bf16(h[2], h[3]); o8[64 * j] = w; }
	v_add_f32_e32 v176, v176, v177
	ds_bpermute_b32 v177, v202, v176
	s_waitcnt lgkmcnt(0)
	v_add_f32_e32 v176, v176, v177
	v_fmamk_f32 v176, v176, 0x3a800000, v204
	v_mul_f32_e32 v179, 0x4f800000, v176
	v_cmp_gt_f32_e32 vcc, s20, v176
	s_nop 1
	v_cndmask_b32_e32 v176, v176, v179, vcc
	v_sqrt_f32_e32 v179, v176
	s_nop 0
	v_add_u32_e32 v180, -1, v179
	v_add_u32_e32 v181, 1, v179
	v_fma_f32 v182, -v180, v179, v176
	v_fma_f32 v183, -v181, v179, v176
	v_cmp_ge_f32_e64 s[0:1], 0, v182
	s_nop 1
	v_cndmask_b32_e64 v179, v179, v180, s[0:1]
	v_cmp_lt_f32_e64 s[0:1], 0, v183
	s_nop 1
	v_cndmask_b32_e64 v179, v179, v181, s[0:1]
	v_mul_f32_e32 v180, 0x37800000, v179
	v_cndmask_b32_e32 v179, v179, v180, vcc
	v_cmp_class_f32_e32 vcc, v176, v203
	s_nop 1
	v_cndmask_b32_e32 v176, v179, v176, vcc
	v_div_scale_f32 v179, s[0:1], v176, v176, 1.0
	v_rcp_f32_e32 v180, v179
	v_div_scale_f32 v181, vcc, 1.0, v176, 1.0
	v_fma_f32 v182, -v179, v180, 1.0
	v_fmac_f32_e32 v180, v182, v180
	v_mul_f32_e32 v182, v181, v180
	v_fma_f32 v183, -v179, v182, v181
	v_fmac_f32_e32 v182, v183, v180
	v_fma_f32 v179, -v179, v182, v181
	v_div_fmas_f32 v179, v179, v180, v182
	v_div_fixup_f32 v206, v179, v176, 1.0
	v_pk_mul_f32 v[160:161], v[160:161], v[206:207] op_sel_hi:[1,0]
	v_pk_mul_f32 v[162:163], v[162:163], v[206:207] op_sel_hi:[1,0]
	v_pk_mul_f32 v[160:161], v[64:65], v[160:161]
	v_pk_mul_f32 v[162:163], v[66:67], v[162:163]
	v_pk_fma_f32 v[160:161], v[80:81], v[160:161], v[96:97]
	v_pk_fma_f32 v[162:163], v[82:83], v[162:163], v[98:99]
	v_cvt_pk_bf16_f32 v192, v160, v161
	v_cvt_pk_bf16_f32 v193, v162, v163
	global_store_dwordx2 v34, v[192:193], s[16:17]
	v_pk_mul_f32 v[164:165], v[164:165], v[206:207] op_sel_hi:[1,0]
	v_pk_mul_f32 v[166:167], v[166:167], v[206:207] op_sel_hi:[1,0]
	v_pk_mul_f32 v[164:165], v[68:69], v[164:165]
	v_pk_mul_f32 v[166:167], v[70:71], v[166:167]
	v_pk_fma_f32 v[164:165], v[84:85], v[164:165], v[100:101]
	v_pk_fma_f32 v[166:167], v[86:87], v[166:167], v[102:103]
	v_cvt_pk_bf16_f32 v194, v164, v165
	v_cvt_pk_bf16_f32 v195, v166, v167
	global_store_dwordx2 v34, v[194:195], s[16:17] offset:512
	v_pk_mul_f32 v[168:169], v[168:169], v[206:207] op_sel_hi:[1,0]
	v_pk_mul_f32 v[170:171], v[170:171], v[206:207] op_sel_hi:[1,0]
	v_pk_mul_f32 v[168:169], v[72:73], v[168:169]
	v_pk_mul_f32 v[170:171], v[74:75], v[170:171]
	v_pk_fma_f32 v[168:169], v[88:89], v[168:169], v[104:105]
	v_pk_fma_f32 v[170:171], v[90:91], v[170:171], v[106:107]
	v_cvt_pk_bf16_f32 v196, v168, v169
	v_cvt_pk_bf16_f32 v197, v170, v171
	global_store_dwordx2 v34, v[196:197], s[16:17] offset:1024
	v_pk_mul_f32 v[172:173], v[172:173], v[206:207] op_sel_hi:[1,0]
	v_pk_mul_f32 v[174:175], v[174:175], v[206:207] op_sel_hi:[1,0]
	v_pk_mul_f32 v[172:173], v[76:77], v[172:173]
	v_pk_mul_f32 v[174:175], v[78:79], v[174:175]
	v_pk_fma_f32 v[172:173], v[92:93], v[172:173], v[108:109]
	v_pk_fma_f32 v[174:175], v[94:95], v[174:175], v[110:111]
	v_cvt_pk_bf16_f32 v198, v172, v173
	v_cvt_pk_bf16_f32 v199, v174, v175
	global_store_dwordx2 v34, v[198:199], s[16:17] offset:1536
	s_add_u32 s16, s16, 0x100000
	s_addc_u32 s17, s17, 0
